# K-split sample-row up-GEMM applied to all four up-GEMM phases (was phase 1 only)
# speedup vs baseline: 1.0198x; 1.0198x over previous
; __device__ __forceinline__ int opq_tid() { int t = threadIdx.x; asm volatile("" : "+v"(t)); return t; }
; __device__ __forceinline__ int opq_bid() { int b = blockIdx.x; asm volatile("" : "+s"(b)); return b; }
; #define SK_LOAD(AR, BR, k0) do { _Pragma("unroll") for (int i = 0; i < UNR; ++i) { AR[i] = *(const bf16x8*)(ap + (k0) + 32 * i); \
;             _Pragma("unroll") for (int g = 0; g < NG; ++g) BR[g][i] = *(const bf16x8*)(bp[g] + (k0) + 32 * i); } } while (0)
; #define SK_MMA(AR, BR) do { _Pragma("unroll") for (int i = 0; i < UNR; ++i) _Pragma("unroll") for (int g = 0; g < NG; ++g) acc[g] = __builtin_amdgcn_mfma_f32_16x16x32_bf16(BR[g][i], AR[i], acc[g], 0, 0, 0); } while (0)
;     const int tid = opq_tid(), lane = tid & 63, w = tid >> 6, rr = lane & 15, kq = lane >> 4;
;     const int rg = KS == 2 ? (w & 3) : w, kh = KS == 2 ? (w >> 2) : 0, KL = K / KS;
;     for (int u = (opq_bid() + (int)gridDim.x - bshift) % (int)gridDim.x; u < 2 * KS * ngroups; u += gridDim.x) {
;         const int hv = u & (2 * KS - 1), cg = u / (2 * KS), srow = hv * (128 / KS) + rg * 16 + rr;
;         const bf16_t* ap = A + (size_t)srow * K + kh * KL + 8 * kq;
;         const bf16_t* bp[NG]; f32x4 acc[NG];
; #pragma unroll
;         for (int g = 0; g < NG; ++g) { bp[g] = Bt + (size_t)(Epi::brow(cg, g) + rr) * K + kh * KL + 8 * kq; acc[g] = (f32x4){0.f, 0.f, 0.f, 0.f}; }
;         bf16x8 a0[UNR], a1[UNR], b0[NG][UNR], b1[NG][UNR];
;     ...
;         SK_LOAD(a0, b0, 0);
;         for (int k = 0; k < KL; k += 64 * UNR) {
;             SK_LOAD(a1, b1, k + 32 * UNR);
;             SK_MMA(a0, b0);
;             if (k + 64 * UNR < KL) SK_LOAD(a0, b0, k + 64 * UNR);
;             SK_MMA(a1, b1);
;         }
.Lsku_beg0:
	v_lshl_add_u64 v[72:73], v[62:63], 0, v[10:11]
	v_lshl_add_u64 v[70:71], v[62:63], 0, v[12:13]
	v_lshlrev_b64 v[24:25], 11, v[14:15]
	v_lshl_add_u64 v[74:75], v[62:63], 0, v[24:25]
	s_ashr_i32 s1, s0, 31
	s_add_i32 s3, s3, s6
	s_add_i32 s2, s2, s94
	s_cmpk_lt_i32 s2, 0xb0
	v_lshrrev_b32_e32 v228, 6, v254
	v_and_b32_e32 v229, 3, v228
	v_lshrrev_b32_e32 v230, 2, v228
	v_and_b32_e32 v231, 0x80, v32
	v_lshl_add_u32 v231, v230, 6, v231
	v_add_u32_e32 v231, v231, v78
	v_lshlrev_b32_e32 v232, 9, v229
	v_mov_b32_e32 v233, 0
	v_mov_b32_e32 v235, 0
	v_lshl_add_u64 v[68:69], v[68:69], 0, v[232:233]
	v_lshl_add_u64 v[72:73], v[72:73], 0, v[232:233]
	v_lshl_add_u64 v[70:71], v[70:71], 0, v[232:233]
	v_lshl_add_u64 v[74:75], v[74:75], 0, v[232:233]
	v_add_u32_e32 v234, 0, v231
	v_lshlrev_b32_e32 v234, 11, v234
	v_lshl_add_u64 v[220:221], v[234:235], 0, v[64:65]
	v_lshl_add_u64 v[220:221], v[220:221], 0, v[232:233]
	v_add_u32_e32 v234, 16, v231
	v_lshlrev_b32_e32 v234, 11, v234
	v_lshl_add_u64 v[222:223], v[234:235], 0, v[64:65]
	v_lshl_add_u64 v[222:223], v[222:223], 0, v[232:233]
	v_add_u32_e32 v234, 32, v231
	v_lshlrev_b32_e32 v234, 11, v234
	v_lshl_add_u64 v[224:225], v[234:235], 0, v[64:65]
	v_lshl_add_u64 v[224:225], v[224:225], 0, v[232:233]
	v_add_u32_e32 v234, 48, v231
	v_lshlrev_b32_e32 v234, 11, v234
	v_lshl_add_u64 v[226:227], v[234:235], 0, v[64:65]
	v_lshl_add_u64 v[226:227], v[226:227], 0, v[232:233]
	v_lshl_add_u32 v236, v229, 4, v231
	v_and_b32_e32 v244, 63, v254
	v_lshlrev_b32_e32 v244, 4, v244
	v_lshl_add_u32 v240, v228, 14, v244
	v_lshl_add_u32 v241, v230, 16, v244
	v_lshl_add_u32 v241, v229, 12, v241
	global_load_dwordx4 v[0:3], v[220:221], off
	global_load_dwordx4 v[4:7], v[222:223], off
	global_load_dwordx4 v[8:11], v[224:225], off
	global_load_dwordx4 v[12:15], v[226:227], off
	global_load_dwordx4 v[16:19], v[68:69], off
	global_load_dwordx4 v[20:23], v[72:73], off
	global_load_dwordx4 v[24:27], v[70:71], off
	global_load_dwordx4 v[28:31], v[74:75], off
	global_load_dwordx4 v[36:39], v[220:221], off offset:64
	global_load_dwordx4 v[40:43], v[222:223], off offset:64
	global_load_dwordx4 v[44:47], v[224:225], off offset:64
	global_load_dwordx4 v[48:51], v[226:227], off offset:64
	global_load_dwordx4 v[52:55], v[68:69], off offset:64
	global_load_dwordx4 v[56:59], v[72:73], off offset:64
	global_load_dwordx4 v[148:151], v[70:71], off offset:64
	global_load_dwordx4 v[152:155], v[74:75], off offset:64
	global_load_dwordx4 v[156:159], v[220:221], off offset:128
	global_load_dwordx4 v[160:163], v[222:223], off offset:128
	global_load_dwordx4 v[164:167], v[224:225], off offset:128
	global_load_dwordx4 v[168:171], v[226:227], off offset:128
	global_load_dwordx4 v[172:175], v[68:69], off offset:128
	global_load_dwordx4 v[176:179], v[72:73], off offset:128
	global_load_dwordx4 v[180:183], v[70:71], off offset:128
	global_load_dwordx4 v[184:187], v[74:75], off offset:128
	global_load_dwordx4 v[188:191], v[220:221], off offset:192
	global_load_dwordx4 v[192:195], v[222:223], off offset:192
	global_load_dwordx4 v[196:199], v[224:225], off offset:192
	global_load_dwordx4 v[200:203], v[226:227], off offset:192
	global_load_dwordx4 v[204:207], v[68:69], off offset:192
	global_load_dwordx4 v[208:211], v[72:73], off offset:192
	global_load_dwordx4 v[212:215], v[70:71], off offset:192
	global_load_dwordx4 v[216:219], v[74:75], off offset:192
	s_waitcnt vmcnt(24)
	v_mfma_f32_16x16x32_bf16 v[84:87], v[16:19], v[0:3], 0
	v_mfma_f32_16x16x32_bf16 v[88:91], v[20:23], v[0:3], 0
	v_mfma_f32_16x16x32_bf16 v[92:95], v[24:27], v[0:3], 0
	v_mfma_f32_16x16x32_bf16 v[96:99], v[28:31], v[0:3], 0
	v_mfma_f32_16x16x32_bf16 v[100:103], v[16:19], v[4:7], 0
	v_mfma_f32_16x16x32_bf16 v[104:107], v[20:23], v[4:7], 0
	v_mfma_f32_16x16x32_bf16 v[108:111], v[24:27], v[4:7], 0
	v_mfma_f32_16x16x32_bf16 v[112:115], v[28:31], v[4:7], 0
	v_mfma_f32_16x16x32_bf16 v[116:119], v[16:19], v[8:11], 0
	v_mfma_f32_16x16x32_bf16 v[120:123], v[20:23], v[8:11], 0
	v_mfma_f32_16x16x32_bf16 v[124:127], v[24:27], v[8:11], 0
	v_mfma_f32_16x16x32_bf16 v[128:131], v[28:31], v[8:11], 0
	v_mfma_f32_16x16x32_bf16 v[132:135], v[16:19], v[12:15], 0
	v_mfma_f32_16x16x32_bf16 v[136:139], v[20:23], v[12:15], 0
	v_mfma_f32_16x16x32_bf16 v[140:143], v[24:27], v[12:15], 0
	v_mfma_f32_16x16x32_bf16 v[144:147], v[28:31], v[12:15], 0
	global_load_dwordx4 v[0:3], v[220:221], off offset:256
	global_load_dwordx4 v[4:7], v[222:223], off offset:256
	global_load_dwordx4 v[8:11], v[224:225], off offset:256
	global_load_dwordx4 v[12:15], v[226:227], off offset:256
	global_load_dwordx4 v[16:19], v[68:69], off offset:256
	global_load_dwordx4 v[20:23], v[72:73], off offset:256
	global_load_dwordx4 v[24:27], v[70:71], off offset:256
	global_load_dwordx4 v[28:31], v[74:75], off offset:256
	s_waitcnt vmcnt(24)
	v_mfma_f32_16x16x32_bf16 v[84:87], v[52:55], v[36:39], v[84:87]
	v_mfma_f32_16x16x32_bf16 v[88:91], v[56:59], v[36:39], v[88:91]
	v_mfma_f32_16x16x32_bf16 v[92:95], v[148:151], v[36:39], v[92:95]
	v_mfma_f32_16x16x32_bf16 v[96:99], v[152:155], v[36:39], v[96:99]
	v_mfma_f32_16x16x32_bf16 v[100:103], v[52:55], v[40:43], v[100:103]
	v_mfma_f32_16x16x32_bf16 v[104:107], v[56:59], v[40:43], v[104:107]
	v_mfma_f32_16x16x32_bf16 v[108:111], v[148:151], v[40:43], v[108:111]
	v_mfma_f32_16x16x32_bf16 v[112:115], v[152:155], v[40:43], v[112:115]
	v_mfma_f32_16x16x32_bf16 v[116:119], v[52:55], v[44:47], v[116:119]
	v_mfma_f32_16x16x32_bf16 v[120:123], v[56:59], v[44:47], v[120:123]
	v_mfma_f32_16x16x32_bf16 v[124:127], v[148:151], v[44:47], v[124:127]
	v_mfma_f32_16x16x32_bf16 v[128:131], v[152:155], v[44:47], v[128:131]
	v_mfma_f32_16x16x32_bf16 v[132:135], v[52:55], v[48:51], v[132:135]
	v_mfma_f32_16x16x32_bf16 v[136:139], v[56:59], v[48:51], v[136:139]
	v_mfma_f32_16x16x32_bf16 v[140:143], v[148:151], v[48:51], v[140:143]
	v_mfma_f32_16x16x32_bf16 v[144:147], v[152:155], v[48:51], v[144:147]
	global_load_dwordx4 v[36:39], v[220:221], off offset:320
	global_load_dwordx4 v[40:43], v[222:223], off offset:320
	global_load_dwordx4 v[44:47], v[224:225], off offset:320
	global_load_dwordx4 v[48:51], v[226:227], off offset:320
	global_load_dwordx4 v[52:55], v[68:69], off offset:320
	global_load_dwordx4 v[56:59], v[72:73], off offset:320
	global_load_dwordx4 v[148:151], v[70:71], off offset:320
	global_load_dwordx4 v[152:155], v[74:75], off offset:320
	s_waitcnt vmcnt(24)
; #define SK_LOAD(AR, BR, k0) do { _Pragma("unroll") for (int i = 0; i < UNR; ++i) { AR[i] = *(const bf16x8*)(ap + (k0) + 32 * i); \
;             _Pragma("unroll") for (int g = 0; g < NG; ++g) BR[g][i] = *(const bf16x8*)(bp[g] + (k0) + 32 * i); } } while (0)
; #define SK_MMA(AR, BR) do { _Pragma("unroll") for (int i = 0; i < UNR; ++i) _Pragma("unroll") for (int g = 0; g < NG; ++g) acc[g] = __builtin_amdgcn_mfma_f32_16x16x32_bf16(BR[g][i], AR[i], acc[g], 0, 0, 0); } while (0)
;     ...
;         for (int k = 0; k < KL; k += 64 * UNR) {
;             SK_LOAD(a1, b1, k + 32 * UNR);
;             SK_MMA(a0, b0);
;             if (k + 64 * UNR < KL) SK_LOAD(a0, b0, k + 64 * UNR);
;             SK_MMA(a1, b1);
;         }
	v_mfma_f32_16x16x32_bf16 v[84:87], v[172:175], v[156:159], v[84:87]
	v_mfma_f32_16x16x32_bf16 v[88:91], v[176:179], v[156:159], v[88:91]
	v_mfma_f32_16x16x32_bf16 v[92:95], v[180:183], v[156:159], v[92:95]
	v_mfma_f32_16x16x32_bf16 v[96:99], v[184:187], v[156:159], v[96:99]
	v_mfma_f32_16x16x32_bf16 v[100:103], v[172:175], v[160:163], v[100:103]
	v_mfma_f32_16x16x32_bf16 v[104:107], v[176:179], v[160:163], v[104:107]
	v_mfma_f32_16x16x32_bf16 v[108:111], v[180:183], v[160:163], v[108:111]
	v_mfma_f32_16x16x32_bf16 v[112:115], v[184:187], v[160:163], v[112:115]
	v_mfma_f32_16x16x32_bf16 v[116:119], v[172:175], v[164:167], v[116:119]
	v_mfma_f32_16x16x32_bf16 v[120:123], v[176:179], v[164:167], v[120:123]
	v_mfma_f32_16x16x32_bf16 v[124:127], v[180:183], v[164:167], v[124:127]
	v_mfma_f32_16x16x32_bf16 v[128:131], v[184:187], v[164:167], v[128:131]
	v_mfma_f32_16x16x32_bf16 v[132:135], v[172:175], v[168:171], v[132:135]
	v_mfma_f32_16x16x32_bf16 v[136:139], v[176:179], v[168:171], v[136:139]
	v_mfma_f32_16x16x32_bf16 v[140:143], v[180:183], v[168:171], v[140:143]
	v_mfma_f32_16x16x32_bf16 v[144:147], v[184:187], v[168:171], v[144:147]
	global_load_dwordx4 v[156:159], v[220:221], off offset:384
	global_load_dwordx4 v[160:163], v[222:223], off offset:384
	global_load_dwordx4 v[164:167], v[224:225], off offset:384
	global_load_dwordx4 v[168:171], v[226:227], off offset:384
	global_load_dwordx4 v[172:175], v[68:69], off offset:384
	global_load_dwordx4 v[176:179], v[72:73], off offset:384
	global_load_dwordx4 v[180:183], v[70:71], off offset:384
	global_load_dwordx4 v[184:187], v[74:75], off offset:384
	s_waitcnt vmcnt(24)
	v_mfma_f32_16x16x32_bf16 v[84:87], v[204:207], v[188:191], v[84:87]
	v_mfma_f32_16x16x32_bf16 v[88:91], v[208:211], v[188:191], v[88:91]
	v_mfma_f32_16x16x32_bf16 v[92:95], v[212:215], v[188:191], v[92:95]
	v_mfma_f32_16x16x32_bf16 v[96:99], v[216:219], v[188:191], v[96:99]
	v_mfma_f32_16x16x32_bf16 v[100:103], v[204:207], v[192:195], v[100:103]
	v_mfma_f32_16x16x32_bf16 v[104:107], v[208:211], v[192:195], v[104:107]
	v_mfma_f32_16x16x32_bf16 v[108:111], v[212:215], v[192:195], v[108:111]
	v_mfma_f32_16x16x32_bf16 v[112:115], v[216:219], v[192:195], v[112:115]
	v_mfma_f32_16x16x32_bf16 v[116:119], v[204:207], v[196:199], v[116:119]
	v_mfma_f32_16x16x32_bf16 v[120:123], v[208:211], v[196:199], v[120:123]
	v_mfma_f32_16x16x32_bf16 v[124:127], v[212:215], v[196:199], v[124:127]
	v_mfma_f32_16x16x32_bf16 v[128:131], v[216:219], v[196:199], v[128:131]
	v_mfma_f32_16x16x32_bf16 v[132:135], v[204:207], v[200:203], v[132:135]
	v_mfma_f32_16x16x32_bf16 v[136:139], v[208:211], v[200:203], v[136:139]
	v_mfma_f32_16x16x32_bf16 v[140:143], v[212:215], v[200:203], v[140:143]
	v_mfma_f32_16x16x32_bf16 v[144:147], v[216:219], v[200:203], v[144:147]
	global_load_dwordx4 v[188:191], v[220:221], off offset:448
	global_load_dwordx4 v[192:195], v[222:223], off offset:448
	global_load_dwordx4 v[196:199], v[224:225], off offset:448
	global_load_dwordx4 v[200:203], v[226:227], off offset:448
	global_load_dwordx4 v[204:207], v[68:69], off offset:448
	global_load_dwordx4 v[208:211], v[72:73], off offset:448
	global_load_dwordx4 v[212:215], v[70:71], off offset:448
	global_load_dwordx4 v[216:219], v[74:75], off offset:448
	s_waitcnt vmcnt(24)
	v_mfma_f32_16x16x32_bf16 v[84:87], v[16:19], v[0:3], v[84:87]
	v_mfma_f32_16x16x32_bf16 v[88:91], v[20:23], v[0:3], v[88:91]
	v_mfma_f32_16x16x32_bf16 v[92:95], v[24:27], v[0:3], v[92:95]
	v_mfma_f32_16x16x32_bf16 v[96:99], v[28:31], v[0:3], v[96:99]
	v_mfma_f32_16x16x32_bf16 v[100:103], v[16:19], v[4:7], v[100:103]
	v_mfma_f32_16x16x32_bf16 v[104:107], v[20:23], v[4:7], v[104:107]
	v_mfma_f32_16x16x32_bf16 v[108:111], v[24:27], v[4:7], v[108:111]
	v_mfma_f32_16x16x32_bf16 v[112:115], v[28:31], v[4:7], v[112:115]
	v_mfma_f32_16x16x32_bf16 v[116:119], v[16:19], v[8:11], v[116:119]
	v_mfma_f32_16x16x32_bf16 v[120:123], v[20:23], v[8:11], v[120:123]
	v_mfma_f32_16x16x32_bf16 v[124:127], v[24:27], v[8:11], v[124:127]
	v_mfma_f32_16x16x32_bf16 v[128:131], v[28:31], v[8:11], v[128:131]
	v_mfma_f32_16x16x32_bf16 v[132:135], v[16:19], v[12:15], v[132:135]
	v_mfma_f32_16x16x32_bf16 v[136:139], v[20:23], v[12:15], v[136:139]
	v_mfma_f32_16x16x32_bf16 v[140:143], v[24:27], v[12:15], v[140:143]
	v_mfma_f32_16x16x32_bf16 v[144:147], v[28:31], v[12:15], v[144:147]
	s_waitcnt vmcnt(16)
	v_mfma_f32_16x16x32_bf16 v[84:87], v[52:55], v[36:39], v[84:87]
	v_mfma_f32_16x16x32_bf16 v[88:91], v[56:59], v[36:39], v[88:91]
	v_mfma_f32_16x16x32_bf16 v[92:95], v[148:151], v[36:39], v[92:95]
	v_mfma_f32_16x16x32_bf16 v[96:99], v[152:155], v[36:39], v[96:99]
	v_mfma_f32_16x16x32_bf16 v[100:103], v[52:55], v[40:43], v[100:103]
	v_mfma_f32_16x16x32_bf16 v[104:107], v[56:59], v[40:43], v[104:107]
	v_mfma_f32_16x16x32_bf16 v[108:111], v[148:151], v[40:43], v[108:111]
	v_mfma_f32_16x16x32_bf16 v[112:115], v[152:155], v[40:43], v[112:115]
	v_mfma_f32_16x16x32_bf16 v[116:119], v[52:55], v[44:47], v[116:119]
	v_mfma_f32_16x16x32_bf16 v[120:123], v[56:59], v[44:47], v[120:123]
	v_mfma_f32_16x16x32_bf16 v[124:127], v[148:151], v[44:47], v[124:127]
	v_mfma_f32_16x16x32_bf16 v[128:131], v[152:155], v[44:47], v[128:131]
	v_mfma_f32_16x16x32_bf16 v[132:135], v[52:55], v[48:51], v[132:135]
	v_mfma_f32_16x16x32_bf16 v[136:139], v[56:59], v[48:51], v[136:139]
	v_mfma_f32_16x16x32_bf16 v[140:143], v[148:151], v[48:51], v[140:143]
	v_mfma_f32_16x16x32_bf16 v[144:147], v[152:155], v[48:51], v[144:147]
	s_waitcnt vmcnt(8)
; #define LAS __attribute__((address_space(3)))
; #define SK_LOAD(AR, BR, k0) do { _Pragma("unroll") for (int i = 0; i < UNR; ++i) { AR[i] = *(const bf16x8*)(ap + (k0) + 32 * i); \
;             _Pragma("unroll") for (int g = 0; g < NG; ++g) BR[g][i] = *(const bf16x8*)(bp[g] + (k0) + 32 * i); } } while (0)
; #define SK_MMA(AR, BR) do { _Pragma("unroll") for (int i = 0; i < UNR; ++i) _Pragma("unroll") for (int g = 0; g < NG; ++g) acc[g] = __builtin_amdgcn_mfma_f32_16x16x32_bf16(BR[g][i], AR[i], acc[g], 0, 0, 0); } while (0)
;     ...
;         for (int k = 0; k < KL; k += 64 * UNR) {
;             SK_LOAD(a1, b1, k + 32 * UNR);
;             SK_MMA(a0, b0);
;             if (k + 64 * UNR < KL) SK_LOAD(a0, b0, k + 64 * UNR);
;             SK_MMA(a1, b1);
;         }
;     ...
;         if constexpr (KS == 2) {
;             LAS f32x4* xch = (LAS f32x4*)lds;
;             if (kh == 1) xch[rg * 64 + lane] = acc[0] + (f32x4){0.f, 0.f, 0.f, 0.f};
;             __syncthreads();
;             if (kh == 0) { acc[0] += xch[rg * 64 + lane]; E(acc, srow, cg, kq); }
; __device__ __forceinline__ float rs_sample(const float* ssps, int srow) { return rs_from(ssps + (size_t)srow * 64, 16, 1.0f / 1024.0f); }
	v_mfma_f32_16x16x32_bf16 v[84:87], v[172:175], v[156:159], v[84:87]
	v_mfma_f32_16x16x32_bf16 v[88:91], v[176:179], v[156:159], v[88:91]
	v_mfma_f32_16x16x32_bf16 v[92:95], v[180:183], v[156:159], v[92:95]
	v_mfma_f32_16x16x32_bf16 v[96:99], v[184:187], v[156:159], v[96:99]
	v_mfma_f32_16x16x32_bf16 v[100:103], v[172:175], v[160:163], v[100:103]
	v_mfma_f32_16x16x32_bf16 v[104:107], v[176:179], v[160:163], v[104:107]
	v_mfma_f32_16x16x32_bf16 v[108:111], v[180:183], v[160:163], v[108:111]
	v_mfma_f32_16x16x32_bf16 v[112:115], v[184:187], v[160:163], v[112:115]
	v_mfma_f32_16x16x32_bf16 v[116:119], v[172:175], v[164:167], v[116:119]
	v_mfma_f32_16x16x32_bf16 v[120:123], v[176:179], v[164:167], v[120:123]
	v_mfma_f32_16x16x32_bf16 v[124:127], v[180:183], v[164:167], v[124:127]
	v_mfma_f32_16x16x32_bf16 v[128:131], v[184:187], v[164:167], v[128:131]
	v_mfma_f32_16x16x32_bf16 v[132:135], v[172:175], v[168:171], v[132:135]
	v_mfma_f32_16x16x32_bf16 v[136:139], v[176:179], v[168:171], v[136:139]
	v_mfma_f32_16x16x32_bf16 v[140:143], v[180:183], v[168:171], v[140:143]
	v_mfma_f32_16x16x32_bf16 v[144:147], v[184:187], v[168:171], v[144:147]
	s_waitcnt vmcnt(0)
	v_mfma_f32_16x16x32_bf16 v[84:87], v[204:207], v[188:191], v[84:87]
	v_mfma_f32_16x16x32_bf16 v[88:91], v[208:211], v[188:191], v[88:91]
	v_mfma_f32_16x16x32_bf16 v[92:95], v[212:215], v[188:191], v[92:95]
	v_mfma_f32_16x16x32_bf16 v[96:99], v[216:219], v[188:191], v[96:99]
	v_mfma_f32_16x16x32_bf16 v[100:103], v[204:207], v[192:195], v[100:103]
	v_mfma_f32_16x16x32_bf16 v[104:107], v[208:211], v[192:195], v[104:107]
	v_mfma_f32_16x16x32_bf16 v[108:111], v[212:215], v[192:195], v[108:111]
	v_mfma_f32_16x16x32_bf16 v[112:115], v[216:219], v[192:195], v[112:115]
	v_mfma_f32_16x16x32_bf16 v[116:119], v[204:207], v[196:199], v[116:119]
	v_mfma_f32_16x16x32_bf16 v[120:123], v[208:211], v[196:199], v[120:123]
	v_mfma_f32_16x16x32_bf16 v[124:127], v[212:215], v[196:199], v[124:127]
	v_mfma_f32_16x16x32_bf16 v[128:131], v[216:219], v[196:199], v[128:131]
	v_mfma_f32_16x16x32_bf16 v[132:135], v[204:207], v[200:203], v[132:135]
	v_mfma_f32_16x16x32_bf16 v[136:139], v[208:211], v[200:203], v[136:139]
	v_mfma_f32_16x16x32_bf16 v[140:143], v[212:215], v[200:203], v[140:143]
	v_mfma_f32_16x16x32_bf16 v[144:147], v[216:219], v[200:203], v[144:147]
	v_lshlrev_b32_e32 v234, 8, v236
	v_lshl_add_u64 v[238:239], v[234:235], 0, s[92:93]
	v_lshl_add_u64 v[238:239], v[60:61], 3, v[238:239]
	global_load_dwordx4 v[8:11], v[238:239], off
	global_load_dwordx4 v[12:15], v[238:239], off offset:16
	global_load_dwordx4 v[16:19], v[238:239], off offset:32
	global_load_dwordx4 v[20:23], v[238:239], off offset:48
	s_nop 7
	ds_write_b128 v240, v[84:87] offset:0
	ds_write_b128 v240, v[88:91] offset:1024
	ds_write_b128 v240, v[92:95] offset:2048
	ds_write_b128 v240, v[96:99] offset:3072
	ds_write_b128 v240, v[100:103] offset:4096
	ds_write_b128 v240, v[104:107] offset:5120
	ds_write_b128 v240, v[108:111] offset:6144
	ds_write_b128 v240, v[112:115] offset:7168
	ds_write_b128 v240, v[116:119] offset:8192
	ds_write_b128 v240, v[120:123] offset:9216
	ds_write_b128 v240, v[124:127] offset:10240
	ds_write_b128 v240, v[128:131] offset:11264
	ds_write_b128 v240, v[132:135] offset:12288
	ds_write_b128 v240, v[136:139] offset:13312
	ds_write_b128 v240, v[140:143] offset:14336
	ds_write_b128 v240, v[144:147] offset:15360
	s_waitcnt lgkmcnt(0)
	s_barrier
	ds_read_b128 v[148:151], v241 offset:0
	ds_read_b128 v[152:155], v241 offset:16384
	ds_read_b128 v[156:159], v241 offset:32768
	ds_read_b128 v[160:163], v241 offset:49152
	ds_read_b128 v[164:167], v241 offset:1024
	ds_read_b128 v[168:171], v241 offset:17408
	ds_read_b128 v[172:175], v241 offset:33792
	ds_read_b128 v[176:179], v241 offset:50176
	ds_read_b128 v[180:183], v241 offset:2048
	ds_read_b128 v[184:187], v241 offset:18432
	ds_read_b128 v[188:191], v241 offset:34816
	ds_read_b128 v[192:195], v241 offset:51200
	ds_read_b128 v[196:199], v241 offset:3072
	ds_read_b128 v[200:203], v241 offset:19456
	ds_read_b128 v[204:207], v241 offset:35840
	ds_read_b128 v[208:211], v241 offset:52224
	v_add_u32_e32 v244, 0x8000, v236
	v_mad_i64_i32 v[242:243], s[10:11], v244, s8, v[66:67]
	v_lshl_add_u64 v[242:243], s[0:1], 1, v[242:243]
	v_lshl_add_u64 v[242:243], v[242:243], 0, v[60:61]
	v_mbcnt_lo_u32_b32 v245, -1, 0
	v_mbcnt_hi_u32_b32 v245, -1, v245
	v_xor_b32_e32 v246, 16, v245
	v_xor_b32_e32 v247, 32, v245
	v_lshlrev_b32_e32 v246, 2, v246
	v_lshlrev_b32_e32 v247, 2, v247
	s_waitcnt lgkmcnt(0)
	s_barrier
; __device__ __forceinline__ unsigned cvt_pk_bf16(float lo, float hi) { unsigned r; asm volatile("v_cvt_pk_bf16_f32 %0, %1, %2" : "=v"(r) : "v"(lo), "v"(hi)); return r; }
; __device__ __forceinline__ float rs_sample(const float* ssps, int srow) { return rs_from(ssps + (size_t)srow * 64, 16, 1.0f / 1024.0f); }
;     __device__ __forceinline__ void operator()(const f32x4 (&acc)[2], int srow, int cgp, int kq) const { one(acc[0], srow, 2 * cgp, kq); one(acc[1], srow, 2 * cgp + 1, kq); }
; __device__ __forceinline__ float rs_from(const float* p, int n4, float inv_n) {
;     float s = 0.f;
;     for (int i = 0; i < n4; ++i) { const f32x4 v = *(const f32x4*)(p + 4 * i); s += (v[0] + v[1]) + (v[2] + v[3]); }
;     return rsqrtf(s * inv_n + EPS);
;     __device__ __forceinline__ void operator()(const f32x4 (&acc)[4], int srow, int cgp, int kq) const {
;         const float rs = rs_sample(ssps, srow);
; #pragma unroll
;         for (int q = 0; q < 2; ++q) { f32x4 o;
; #pragma unroll
;             for (int j = 0; j < 4; ++j) { const float g = acc[2 * q][j] * rs, up = acc[2 * q + 1][j] * rs; o[j] = g * __builtin_amdgcn_rcpf(1.0f + __expf(-g)) * up; }
;             u32x2 w; w.x = cvt_pk_bf16(o[0], o[1]); w.y = cvt_pk_bf16(o[2], o[3]);
;             *(u32x2*)(act + (size_t)(TP + srow) * FF + (2 * cgp + q) * 16 + 4 * kq) = w; }
	v_add_f32_e32 v84, v148, v152
	v_add_f32_e32 v85, v149, v153
	v_add_f32_e32 v86, v150, v154
	v_add_f32_e32 v87, v151, v155
	v_add_f32_e32 v84, v84, v156
	v_add_f32_e32 v85, v85, v157
	v_add_f32_e32 v86, v86, v158
	v_add_f32_e32 v87, v87, v159
	v_add_f32_e32 v84, v84, v160
	v_add_f32_e32 v85, v85, v161
	v_add_f32_e32 v86, v86, v162
	v_add_f32_e32 v87, v87, v163
	v_add_f32_e32 v88, v164, v168
	v_add_f32_e32 v89, v165, v169
	v_add_f32_e32 v90, v166, v170
	v_add_f32_e32 v91, v167, v171
	v_add_f32_e32 v88, v88, v172
	v_add_f32_e32 v89, v89, v173
	v_add_f32_e32 v90, v90, v174
	v_add_f32_e32 v91, v91, v175
	v_add_f32_e32 v88, v88, v176
	v_add_f32_e32 v89, v89, v177
	v_add_f32_e32 v90, v90, v178
	v_add_f32_e32 v91, v91, v179
	v_add_f32_e32 v92, v180, v184
	v_add_f32_e32 v93, v181, v185
	v_add_f32_e32 v94, v182, v186
	v_add_f32_e32 v95, v183, v187
	v_add_f32_e32 v92, v92, v188
	v_add_f32_e32 v93, v93, v189
	v_add_f32_e32 v94, v94, v190
	v_add_f32_e32 v95, v95, v191
	v_add_f32_e32 v92, v92, v192
	v_add_f32_e32 v93, v93, v193
	v_add_f32_e32 v94, v94, v194
	v_add_f32_e32 v95, v95, v195
	v_add_f32_e32 v96, v196, v200
	v_add_f32_e32 v97, v197, v201
	v_add_f32_e32 v98, v198, v202
	v_add_f32_e32 v99, v199, v203
	v_add_f32_e32 v96, v96, v204
	v_add_f32_e32 v97, v97, v205
	v_add_f32_e32 v98, v98, v206
	v_add_f32_e32 v99, v99, v207
	v_add_f32_e32 v96, v96, v208
	v_add_f32_e32 v97, v97, v209
	v_add_f32_e32 v98, v98, v210
	v_add_f32_e32 v99, v99, v211
	s_waitcnt vmcnt(0)
	v_add_f32_e32 v8, v8, v9
	v_add_f32_e32 v10, v10, v11
	v_add_f32_e32 v8, v8, v10
	v_add_f32_e32 v12, v12, v13
	v_add_f32_e32 v14, v14, v15
	v_add_f32_e32 v12, v12, v14
	v_add_f32_e32 v16, v16, v17
	v_add_f32_e32 v18, v18, v19
	v_add_f32_e32 v16, v16, v18
	v_add_f32_e32 v20, v20, v21
	v_add_f32_e32 v22, v22, v23
	v_add_f32_e32 v20, v20, v22
	v_add_f32_e32 v8, v8, v12
	v_add_f32_e32 v16, v16, v20
	v_add_f32_e32 v8, v8, v16
	ds_bpermute_b32 v9, v246, v8
	s_waitcnt lgkmcnt(0)
	v_add_f32_e32 v8, v8, v9
	ds_bpermute_b32 v9, v247, v8
	s_waitcnt lgkmcnt(0)
	v_add_f32_e32 v8, v8, v9
	v_fmamk_f32 v8, v8, 0x3a800000, v80
	v_rsq_f32_e32 v8, v8
	s_nop 0
	v_pk_mul_f32 v[84:85], v[84:85], v[8:9] op_sel_hi:[1,0]
	v_pk_mul_f32 v[86:87], v[86:87], v[8:9] op_sel_hi:[1,0]
	v_pk_mul_f32 v[88:89], v[88:89], v[8:9] op_sel_hi:[1,0]
	v_pk_mul_f32 v[90:91], v[90:91], v[8:9] op_sel_hi:[1,0]
	v_pk_mul_f32 v[92:93], v[92:93], v[8:9] op_sel_hi:[1,0]
	v_pk_mul_f32 v[94:95], v[94:95], v[8:9] op_sel_hi:[1,0]
	v_pk_mul_f32 v[96:97], v[96:97], v[8:9] op_sel_hi:[1,0]
	v_pk_mul_f32 v[98:99], v[98:99], v[8:9] op_sel_hi:[1,0]
	v_mul_f32_e32 v0, 0xbfb8aa3b, v84
	v_mul_f32_e32 v1, 0xbfb8aa3b, v85
	v_mul_f32_e32 v2, 0xbfb8aa3b, v86
	v_mul_f32_e32 v3, 0xbfb8aa3b, v87
	v_mul_f32_e32 v4, 0xbfb8aa3b, v92
	v_mul_f32_e32 v5, 0xbfb8aa3b, v93
	v_mul_f32_e32 v6, 0xbfb8aa3b, v94
	v_mul_f32_e32 v7, 0xbfb8aa3b, v95
	v_exp_f32_e32 v0, v0
	v_exp_f32_e32 v1, v1
	v_exp_f32_e32 v2, v2
	v_exp_f32_e32 v3, v3
	v_exp_f32_e32 v4, v4
	v_exp_f32_e32 v5, v5
	v_exp_f32_e32 v6, v6
	v_exp_f32_e32 v7, v7
	v_add_f32_e32 v0, 1.0, v0
	v_add_f32_e32 v1, 1.0, v1
	v_add_f32_e32 v2, 1.0, v2
	v_add_f32_e32 v3, 1.0, v3
	v_add_f32_e32 v4, 1.0, v4
	v_add_f32_e32 v5, 1.0, v5
	v_add_f32_e32 v6, 1.0, v6
	v_add_f32_e32 v7, 1.0, v7
	v_rcp_f32_e32 v0, v0
	v_rcp_f32_e32 v1, v1
	v_rcp_f32_e32 v2, v2
	v_rcp_f32_e32 v3, v3
	v_rcp_f32_e32 v4, v4
	v_rcp_f32_e32 v5, v5
	v_rcp_f32_e32 v6, v6
	v_rcp_f32_e32 v7, v7
	v_mul_f32_e32 v0, v84, v0
	v_mul_f32_e32 v1, v85, v1
	v_mul_f32_e32 v2, v86, v2
	v_mul_f32_e32 v3, v87, v3
	v_mul_f32_e32 v4, v92, v4
	v_mul_f32_e32 v5, v93, v5
	v_mul_f32_e32 v6, v94, v6
	v_mul_f32_e32 v7, v95, v7
	v_mul_f32_e32 v0, v88, v0
	v_mul_f32_e32 v1, v89, v1
	v_mul_f32_e32 v2, v90, v2
	v_mul_f32_e32 v3, v91, v3
	v_mul_f32_e32 v4, v96, v4
	v_mul_f32_e32 v5, v97, v5
	v_mul_f32_e32 v6, v98, v6
	v_mul_f32_e32 v7, v99, v7
	v_cvt_pk_bf16_f32 v24, v0, v1
	v_cvt_pk_bf16_f32 v25, v2, v3
	v_cvt_pk_bf16_f32 v26, v4, v5
	v_cvt_pk_bf16_f32 v27, v6, v7
	global_store_dwordx2 v[242:243], v[24:25], off
	global_store_dwordx2 v[242:243], v[26:27], off offset:32

; __device__ __forceinline__ int opq_tid() { int t = threadIdx.x; asm volatile("" : "+v"(t)); return t; }
; __device__ __forceinline__ int opq_bid() { int b = blockIdx.x; asm volatile("" : "+s"(b)); return b; }
; #define SK_LOAD(AR, BR, k0) do { _Pragma("unroll") for (int i = 0; i < UNR; ++i) { AR[i] = *(const bf16x8*)(ap + (k0) + 32 * i); \
;             _Pragma("unroll") for (int g = 0; g < NG; ++g) BR[g][i] = *(const bf16x8*)(bp[g] + (k0) + 32 * i); } } while (0)
; #define SK_MMA(AR, BR) do { _Pragma("unroll") for (int i = 0; i < UNR; ++i) _Pragma("unroll") for (int g = 0; g < NG; ++g) acc[g] = __builtin_amdgcn_mfma_f32_16x16x32_bf16(BR[g][i], AR[i], acc[g], 0, 0, 0); } while (0)
;     const int tid = opq_tid(), lane = tid & 63, w = tid >> 6, rr = lane & 15, kq = lane >> 4;
;     const int rg = KS == 2 ? (w & 3) : w, kh = KS == 2 ? (w >> 2) : 0, KL = K / KS;
;     for (int u = (opq_bid() + (int)gridDim.x - bshift) % (int)gridDim.x; u < 2 * KS * ngroups; u += gridDim.x) {
;         const int hv = u & (2 * KS - 1), cg = u / (2 * KS), srow = hv * (128 / KS) + rg * 16 + rr;
;         const bf16_t* ap = A + (size_t)srow * K + kh * KL + 8 * kq;
;         const bf16_t* bp[NG]; f32x4 acc[NG];
; #pragma unroll
;         for (int g = 0; g < NG; ++g) { bp[g] = Bt + (size_t)(Epi::brow(cg, g) + rr) * K + kh * KL + 8 * kq; acc[g] = (f32x4){0.f, 0.f, 0.f, 0.f}; }
;         bf16x8 a0[UNR], a1[UNR], b0[NG][UNR], b1[NG][UNR];
;     ...
;         SK_LOAD(a0, b0, 0);
;         for (int k = 0; k < KL; k += 64 * UNR) {
;             SK_LOAD(a1, b1, k + 32 * UNR);
;             SK_MMA(a0, b0);
;             if (k + 64 * UNR < KL) SK_LOAD(a0, b0, k + 64 * UNR);
;             SK_MMA(a1, b1);
;         }
.Lsku_beg1:
	v_lshl_add_u64 v[44:45], v[36:37], 0, v[6:7]
	v_lshl_add_u64 v[46:47], v[36:37], 0, v[12:13]
	v_lshlrev_b64 v[16:17], 11, v[14:15]
	v_lshl_add_u64 v[40:41], v[36:37], 0, v[16:17]
	s_ashr_i32 s1, s0, 31
	s_add_i32 s3, s3, s8
	s_add_i32 s2, s2, s94
	s_cmpk_lt_i32 s2, 0xb0
	v_lshrrev_b32_e32 v228, 6, v254
	v_and_b32_e32 v229, 3, v228
	v_lshrrev_b32_e32 v230, 2, v228
	v_and_b32_e32 v231, 0x80, v50
	v_lshl_add_u32 v231, v230, 6, v231
	v_add_u32_e32 v231, v231, v52
	v_lshlrev_b32_e32 v232, 9, v229
	v_mov_b32_e32 v233, 0
	v_mov_b32_e32 v235, 0
	v_lshl_add_u64 v[42:43], v[42:43], 0, v[232:233]
	v_lshl_add_u64 v[44:45], v[44:45], 0, v[232:233]
	v_lshl_add_u64 v[46:47], v[46:47], 0, v[232:233]
	v_lshl_add_u64 v[40:41], v[40:41], 0, v[232:233]
	v_add_u32_e32 v234, 0, v231
	v_lshlrev_b32_e32 v234, 11, v234
	v_lshl_add_u64 v[220:221], v[234:235], 0, v[34:35]
	v_lshl_add_u64 v[220:221], v[220:221], 0, v[232:233]
	v_add_u32_e32 v234, 16, v231
	v_lshlrev_b32_e32 v234, 11, v234
	v_lshl_add_u64 v[222:223], v[234:235], 0, v[34:35]
	v_lshl_add_u64 v[222:223], v[222:223], 0, v[232:233]
	v_add_u32_e32 v234, 32, v231
	v_lshlrev_b32_e32 v234, 11, v234
	v_lshl_add_u64 v[224:225], v[234:235], 0, v[34:35]
	v_lshl_add_u64 v[224:225], v[224:225], 0, v[232:233]
	v_add_u32_e32 v234, 48, v231
	v_lshlrev_b32_e32 v234, 11, v234
	v_lshl_add_u64 v[226:227], v[234:235], 0, v[34:35]
	v_lshl_add_u64 v[226:227], v[226:227], 0, v[232:233]
	v_lshl_add_u32 v236, v229, 4, v231
	v_and_b32_e32 v244, 63, v254
	v_lshlrev_b32_e32 v244, 4, v244
	v_lshl_add_u32 v240, v228, 14, v244
	v_lshl_add_u32 v241, v230, 16, v244
	v_lshl_add_u32 v241, v229, 12, v241
	global_load_dwordx4 v[0:3], v[220:221], off
	global_load_dwordx4 v[4:7], v[222:223], off
	global_load_dwordx4 v[8:11], v[224:225], off
	global_load_dwordx4 v[12:15], v[226:227], off
	global_load_dwordx4 v[16:19], v[42:43], off
	global_load_dwordx4 v[20:23], v[44:45], off
	global_load_dwordx4 v[24:27], v[46:47], off
	global_load_dwordx4 v[28:31], v[40:41], off
	global_load_dwordx4 v[56:59], v[220:221], off offset:64
	global_load_dwordx4 v[60:63], v[222:223], off offset:64
	global_load_dwordx4 v[64:67], v[224:225], off offset:64
	global_load_dwordx4 v[68:71], v[226:227], off offset:64
	global_load_dwordx4 v[72:75], v[42:43], off offset:64
	global_load_dwordx4 v[76:79], v[44:45], off offset:64
	global_load_dwordx4 v[80:83], v[46:47], off offset:64
	global_load_dwordx4 v[148:151], v[40:41], off offset:64
	global_load_dwordx4 v[152:155], v[220:221], off offset:128
	global_load_dwordx4 v[156:159], v[222:223], off offset:128
	global_load_dwordx4 v[160:163], v[224:225], off offset:128
	global_load_dwordx4 v[164:167], v[226:227], off offset:128
	global_load_dwordx4 v[168:171], v[42:43], off offset:128
	global_load_dwordx4 v[172:175], v[44:45], off offset:128
	global_load_dwordx4 v[176:179], v[46:47], off offset:128
	global_load_dwordx4 v[180:183], v[40:41], off offset:128
	global_load_dwordx4 v[184:187], v[220:221], off offset:192
	global_load_dwordx4 v[188:191], v[222:223], off offset:192
	global_load_dwordx4 v[192:195], v[224:225], off offset:192
	global_load_dwordx4 v[196:199], v[226:227], off offset:192
	global_load_dwordx4 v[200:203], v[42:43], off offset:192
	global_load_dwordx4 v[204:207], v[44:45], off offset:192
	global_load_dwordx4 v[208:211], v[46:47], off offset:192
	global_load_dwordx4 v[212:215], v[40:41], off offset:192
	s_waitcnt vmcnt(24)
	v_mfma_f32_16x16x32_bf16 v[84:87], v[16:19], v[0:3], 0
	v_mfma_f32_16x16x32_bf16 v[88:91], v[20:23], v[0:3], 0
	v_mfma_f32_16x16x32_bf16 v[92:95], v[24:27], v[0:3], 0
	v_mfma_f32_16x16x32_bf16 v[96:99], v[28:31], v[0:3], 0
	v_mfma_f32_16x16x32_bf16 v[100:103], v[16:19], v[4:7], 0
	v_mfma_f32_16x16x32_bf16 v[104:107], v[20:23], v[4:7], 0
	v_mfma_f32_16x16x32_bf16 v[108:111], v[24:27], v[4:7], 0
	v_mfma_f32_16x16x32_bf16 v[112:115], v[28:31], v[4:7], 0
	v_mfma_f32_16x16x32_bf16 v[116:119], v[16:19], v[8:11], 0
	v_mfma_f32_16x16x32_bf16 v[120:123], v[20:23], v[8:11], 0
	v_mfma_f32_16x16x32_bf16 v[124:127], v[24:27], v[8:11], 0
	v_mfma_f32_16x16x32_bf16 v[128:131], v[28:31], v[8:11], 0
	v_mfma_f32_16x16x32_bf16 v[132:135], v[16:19], v[12:15], 0
	v_mfma_f32_16x16x32_bf16 v[136:139], v[20:23], v[12:15], 0
	v_mfma_f32_16x16x32_bf16 v[140:143], v[24:27], v[12:15], 0
	v_mfma_f32_16x16x32_bf16 v[144:147], v[28:31], v[12:15], 0
	global_load_dwordx4 v[0:3], v[220:221], off offset:256
	global_load_dwordx4 v[4:7], v[222:223], off offset:256
	global_load_dwordx4 v[8:11], v[224:225], off offset:256
	global_load_dwordx4 v[12:15], v[226:227], off offset:256
	global_load_dwordx4 v[16:19], v[42:43], off offset:256
	global_load_dwordx4 v[20:23], v[44:45], off offset:256
	global_load_dwordx4 v[24:27], v[46:47], off offset:256
	global_load_dwordx4 v[28:31], v[40:41], off offset:256
	s_waitcnt vmcnt(24)
	v_mfma_f32_16x16x32_bf16 v[84:87], v[72:75], v[56:59], v[84:87]
	v_mfma_f32_16x16x32_bf16 v[88:91], v[76:79], v[56:59], v[88:91]
	v_mfma_f32_16x16x32_bf16 v[92:95], v[80:83], v[56:59], v[92:95]
	v_mfma_f32_16x16x32_bf16 v[96:99], v[148:151], v[56:59], v[96:99]
	v_mfma_f32_16x16x32_bf16 v[100:103], v[72:75], v[60:63], v[100:103]
	v_mfma_f32_16x16x32_bf16 v[104:107], v[76:79], v[60:63], v[104:107]
	v_mfma_f32_16x16x32_bf16 v[108:111], v[80:83], v[60:63], v[108:111]
	v_mfma_f32_16x16x32_bf16 v[112:115], v[148:151], v[60:63], v[112:115]
	v_mfma_f32_16x16x32_bf16 v[116:119], v[72:75], v[64:67], v[116:119]
	v_mfma_f32_16x16x32_bf16 v[120:123], v[76:79], v[64:67], v[120:123]
	v_mfma_f32_16x16x32_bf16 v[124:127], v[80:83], v[64:67], v[124:127]
	v_mfma_f32_16x16x32_bf16 v[128:131], v[148:151], v[64:67], v[128:131]
	v_mfma_f32_16x16x32_bf16 v[132:135], v[72:75], v[68:71], v[132:135]
	v_mfma_f32_16x16x32_bf16 v[136:139], v[76:79], v[68:71], v[136:139]
	v_mfma_f32_16x16x32_bf16 v[140:143], v[80:83], v[68:71], v[140:143]
	v_mfma_f32_16x16x32_bf16 v[144:147], v[148:151], v[68:71], v[144:147]
	global_load_dwordx4 v[56:59], v[220:221], off offset:320
	global_load_dwordx4 v[60:63], v[222:223], off offset:320
	global_load_dwordx4 v[64:67], v[224:225], off offset:320
	global_load_dwordx4 v[68:71], v[226:227], off offset:320
	global_load_dwordx4 v[72:75], v[42:43], off offset:320
	global_load_dwordx4 v[76:79], v[44:45], off offset:320
	global_load_dwordx4 v[80:83], v[46:47], off offset:320
	global_load_dwordx4 v[148:151], v[40:41], off offset:320
	s_waitcnt vmcnt(24)
; #define SK_LOAD(AR, BR, k0) do { _Pragma("unroll") for (int i = 0; i < UNR; ++i) { AR[i] = *(const bf16x8*)(ap + (k0) + 32 * i); \
;             _Pragma("unroll") for (int g = 0; g < NG; ++g) BR[g][i] = *(const bf16x8*)(bp[g] + (k0) + 32 * i); } } while (0)
; #define SK_MMA(AR, BR) do { _Pragma("unroll") for (int i = 0; i < UNR; ++i) _Pragma("unroll") for (int g = 0; g < NG; ++g) acc[g] = __builtin_amdgcn_mfma_f32_16x16x32_bf16(BR[g][i], AR[i], acc[g], 0, 0, 0); } while (0)
;     ...
;         for (int k = 0; k < KL; k += 64 * UNR) {
;             SK_LOAD(a1, b1, k + 32 * UNR);
;             SK_MMA(a0, b0);
;             if (k + 64 * UNR < KL) SK_LOAD(a0, b0, k + 64 * UNR);
;             SK_MMA(a1, b1);
;         }
	v_mfma_f32_16x16x32_bf16 v[84:87], v[168:171], v[152:155], v[84:87]
	v_mfma_f32_16x16x32_bf16 v[88:91], v[172:175], v[152:155], v[88:91]
	v_mfma_f32_16x16x32_bf16 v[92:95], v[176:179], v[152:155], v[92:95]
	v_mfma_f32_16x16x32_bf16 v[96:99], v[180:183], v[152:155], v[96:99]
	v_mfma_f32_16x16x32_bf16 v[100:103], v[168:171], v[156:159], v[100:103]
	v_mfma_f32_16x16x32_bf16 v[104:107], v[172:175], v[156:159], v[104:107]
	v_mfma_f32_16x16x32_bf16 v[108:111], v[176:179], v[156:159], v[108:111]
	v_mfma_f32_16x16x32_bf16 v[112:115], v[180:183], v[156:159], v[112:115]
	v_mfma_f32_16x16x32_bf16 v[116:119], v[168:171], v[160:163], v[116:119]
	v_mfma_f32_16x16x32_bf16 v[120:123], v[172:175], v[160:163], v[120:123]
	v_mfma_f32_16x16x32_bf16 v[124:127], v[176:179], v[160:163], v[124:127]
	v_mfma_f32_16x16x32_bf16 v[128:131], v[180:183], v[160:163], v[128:131]
	v_mfma_f32_16x16x32_bf16 v[132:135], v[168:171], v[164:167], v[132:135]
	v_mfma_f32_16x16x32_bf16 v[136:139], v[172:175], v[164:167], v[136:139]
	v_mfma_f32_16x16x32_bf16 v[140:143], v[176:179], v[164:167], v[140:143]
	v_mfma_f32_16x16x32_bf16 v[144:147], v[180:183], v[164:167], v[144:147]
	global_load_dwordx4 v[152:155], v[220:221], off offset:384
	global_load_dwordx4 v[156:159], v[222:223], off offset:384
	global_load_dwordx4 v[160:163], v[224:225], off offset:384
	global_load_dwordx4 v[164:167], v[226:227], off offset:384
	global_load_dwordx4 v[168:171], v[42:43], off offset:384
	global_load_dwordx4 v[172:175], v[44:45], off offset:384
	global_load_dwordx4 v[176:179], v[46:47], off offset:384
	global_load_dwordx4 v[180:183], v[40:41], off offset:384
	s_waitcnt vmcnt(24)
	v_mfma_f32_16x16x32_bf16 v[84:87], v[200:203], v[184:187], v[84:87]
	v_mfma_f32_16x16x32_bf16 v[88:91], v[204:207], v[184:187], v[88:91]
	v_mfma_f32_16x16x32_bf16 v[92:95], v[208:211], v[184:187], v[92:95]
	v_mfma_f32_16x16x32_bf16 v[96:99], v[212:215], v[184:187], v[96:99]
	v_mfma_f32_16x16x32_bf16 v[100:103], v[200:203], v[188:191], v[100:103]
	v_mfma_f32_16x16x32_bf16 v[104:107], v[204:207], v[188:191], v[104:107]
	v_mfma_f32_16x16x32_bf16 v[108:111], v[208:211], v[188:191], v[108:111]
	v_mfma_f32_16x16x32_bf16 v[112:115], v[212:215], v[188:191], v[112:115]
	v_mfma_f32_16x16x32_bf16 v[116:119], v[200:203], v[192:195], v[116:119]
	v_mfma_f32_16x16x32_bf16 v[120:123], v[204:207], v[192:195], v[120:123]
	v_mfma_f32_16x16x32_bf16 v[124:127], v[208:211], v[192:195], v[124:127]
	v_mfma_f32_16x16x32_bf16 v[128:131], v[212:215], v[192:195], v[128:131]
	v_mfma_f32_16x16x32_bf16 v[132:135], v[200:203], v[196:199], v[132:135]
	v_mfma_f32_16x16x32_bf16 v[136:139], v[204:207], v[196:199], v[136:139]
	v_mfma_f32_16x16x32_bf16 v[140:143], v[208:211], v[196:199], v[140:143]
	v_mfma_f32_16x16x32_bf16 v[144:147], v[212:215], v[196:199], v[144:147]
	global_load_dwordx4 v[184:187], v[220:221], off offset:448
	global_load_dwordx4 v[188:191], v[222:223], off offset:448
	global_load_dwordx4 v[192:195], v[224:225], off offset:448
	global_load_dwordx4 v[196:199], v[226:227], off offset:448
	global_load_dwordx4 v[200:203], v[42:43], off offset:448
	global_load_dwordx4 v[204:207], v[44:45], off offset:448
	global_load_dwordx4 v[208:211], v[46:47], off offset:448
	global_load_dwordx4 v[212:215], v[40:41], off offset:448
	s_waitcnt vmcnt(24)
	v_mfma_f32_16x16x32_bf16 v[84:87], v[16:19], v[0:3], v[84:87]
	v_mfma_f32_16x16x32_bf16 v[88:91], v[20:23], v[0:3], v[88:91]
	v_mfma_f32_16x16x32_bf16 v[92:95], v[24:27], v[0:3], v[92:95]
	v_mfma_f32_16x16x32_bf16 v[96:99], v[28:31], v[0:3], v[96:99]
	v_mfma_f32_16x16x32_bf16 v[100:103], v[16:19], v[4:7], v[100:103]
	v_mfma_f32_16x16x32_bf16 v[104:107], v[20:23], v[4:7], v[104:107]
	v_mfma_f32_16x16x32_bf16 v[108:111], v[24:27], v[4:7], v[108:111]
	v_mfma_f32_16x16x32_bf16 v[112:115], v[28:31], v[4:7], v[112:115]
	v_mfma_f32_16x16x32_bf16 v[116:119], v[16:19], v[8:11], v[116:119]
	v_mfma_f32_16x16x32_bf16 v[120:123], v[20:23], v[8:11], v[120:123]
	v_mfma_f32_16x16x32_bf16 v[124:127], v[24:27], v[8:11], v[124:127]
	v_mfma_f32_16x16x32_bf16 v[128:131], v[28:31], v[8:11], v[128:131]
	v_mfma_f32_16x16x32_bf16 v[132:135], v[16:19], v[12:15], v[132:135]
	v_mfma_f32_16x16x32_bf16 v[136:139], v[20:23], v[12:15], v[136:139]
	v_mfma_f32_16x16x32_bf16 v[140:143], v[24:27], v[12:15], v[140:143]
	v_mfma_f32_16x16x32_bf16 v[144:147], v[28:31], v[12:15], v[144:147]
	s_waitcnt vmcnt(16)
	v_mfma_f32_16x16x32_bf16 v[84:87], v[72:75], v[56:59], v[84:87]
	v_mfma_f32_16x16x32_bf16 v[88:91], v[76:79], v[56:59], v[88:91]
	v_mfma_f32_16x16x32_bf16 v[92:95], v[80:83], v[56:59], v[92:95]
	v_mfma_f32_16x16x32_bf16 v[96:99], v[148:151], v[56:59], v[96:99]
	v_mfma_f32_16x16x32_bf16 v[100:103], v[72:75], v[60:63], v[100:103]
	v_mfma_f32_16x16x32_bf16 v[104:107], v[76:79], v[60:63], v[104:107]
	v_mfma_f32_16x16x32_bf16 v[108:111], v[80:83], v[60:63], v[108:111]
	v_mfma_f32_16x16x32_bf16 v[112:115], v[148:151], v[60:63], v[112:115]
	v_mfma_f32_16x16x32_bf16 v[116:119], v[72:75], v[64:67], v[116:119]
	v_mfma_f32_16x16x32_bf16 v[120:123], v[76:79], v[64:67], v[120:123]
	v_mfma_f32_16x16x32_bf16 v[124:127], v[80:83], v[64:67], v[124:127]
	v_mfma_f32_16x16x32_bf16 v[128:131], v[148:151], v[64:67], v[128:131]
	v_mfma_f32_16x16x32_bf16 v[132:135], v[72:75], v[68:71], v[132:135]
	v_mfma_f32_16x16x32_bf16 v[136:139], v[76:79], v[68:71], v[136:139]
	v_mfma_f32_16x16x32_bf16 v[140:143], v[80:83], v[68:71], v[140:143]
	v_mfma_f32_16x16x32_bf16 v[144:147], v[148:151], v[68:71], v[144:147]
	s_waitcnt vmcnt(8)
; #define LAS __attribute__((address_space(3)))
; #define SK_LOAD(AR, BR, k0) do { _Pragma("unroll") for (int i = 0; i < UNR; ++i) { AR[i] = *(const bf16x8*)(ap + (k0) + 32 * i); \
;             _Pragma("unroll") for (int g = 0; g < NG; ++g) BR[g][i] = *(const bf16x8*)(bp[g] + (k0) + 32 * i); } } while (0)
; #define SK_MMA(AR, BR) do { _Pragma("unroll") for (int i = 0; i < UNR; ++i) _Pragma("unroll") for (int g = 0; g < NG; ++g) acc[g] = __builtin_amdgcn_mfma_f32_16x16x32_bf16(BR[g][i], AR[i], acc[g], 0, 0, 0); } while (0)
;     ...
;         for (int k = 0; k < KL; k += 64 * UNR) {
;             SK_LOAD(a1, b1, k + 32 * UNR);
;             SK_MMA(a0, b0);
;             if (k + 64 * UNR < KL) SK_LOAD(a0, b0, k + 64 * UNR);
;             SK_MMA(a1, b1);
;         }
;     ...
;         if constexpr (KS == 2) {
;             LAS f32x4* xch = (LAS f32x4*)lds;
;             if (kh == 1) xch[rg * 64 + lane] = acc[0] + (f32x4){0.f, 0.f, 0.f, 0.f};
;             __syncthreads();
;             if (kh == 0) { acc[0] += xch[rg * 64 + lane]; E(acc, srow, cg, kq); }
; __device__ __forceinline__ float rs_sample(const float* ssps, int srow) { return rs_from(ssps + (size_t)srow * 64, 16, 1.0f / 1024.0f); }
	v_mfma_f32_16x16x32_bf16 v[84:87], v[168:171], v[152:155], v[84:87]
	v_mfma_f32_16x16x32_bf16 v[88:91], v[172:175], v[152:155], v[88:91]
	v_mfma_f32_16x16x32_bf16 v[92:95], v[176:179], v[152:155], v[92:95]
	v_mfma_f32_16x16x32_bf16 v[96:99], v[180:183], v[152:155], v[96:99]
	v_mfma_f32_16x16x32_bf16 v[100:103], v[168:171], v[156:159], v[100:103]
	v_mfma_f32_16x16x32_bf16 v[104:107], v[172:175], v[156:159], v[104:107]
	v_mfma_f32_16x16x32_bf16 v[108:111], v[176:179], v[156:159], v[108:111]
	v_mfma_f32_16x16x32_bf16 v[112:115], v[180:183], v[156:159], v[112:115]
	v_mfma_f32_16x16x32_bf16 v[116:119], v[168:171], v[160:163], v[116:119]
	v_mfma_f32_16x16x32_bf16 v[120:123], v[172:175], v[160:163], v[120:123]
	v_mfma_f32_16x16x32_bf16 v[124:127], v[176:179], v[160:163], v[124:127]
	v_mfma_f32_16x16x32_bf16 v[128:131], v[180:183], v[160:163], v[128:131]
	v_mfma_f32_16x16x32_bf16 v[132:135], v[168:171], v[164:167], v[132:135]
	v_mfma_f32_16x16x32_bf16 v[136:139], v[172:175], v[164:167], v[136:139]
	v_mfma_f32_16x16x32_bf16 v[140:143], v[176:179], v[164:167], v[140:143]
	v_mfma_f32_16x16x32_bf16 v[144:147], v[180:183], v[164:167], v[144:147]
	s_waitcnt vmcnt(0)
	v_mfma_f32_16x16x32_bf16 v[84:87], v[200:203], v[184:187], v[84:87]
	v_mfma_f32_16x16x32_bf16 v[88:91], v[204:207], v[184:187], v[88:91]
	v_mfma_f32_16x16x32_bf16 v[92:95], v[208:211], v[184:187], v[92:95]
	v_mfma_f32_16x16x32_bf16 v[96:99], v[212:215], v[184:187], v[96:99]
	v_mfma_f32_16x16x32_bf16 v[100:103], v[200:203], v[188:191], v[100:103]
	v_mfma_f32_16x16x32_bf16 v[104:107], v[204:207], v[188:191], v[104:107]
	v_mfma_f32_16x16x32_bf16 v[108:111], v[208:211], v[188:191], v[108:111]
	v_mfma_f32_16x16x32_bf16 v[112:115], v[212:215], v[188:191], v[112:115]
	v_mfma_f32_16x16x32_bf16 v[116:119], v[200:203], v[192:195], v[116:119]
	v_mfma_f32_16x16x32_bf16 v[120:123], v[204:207], v[192:195], v[120:123]
	v_mfma_f32_16x16x32_bf16 v[124:127], v[208:211], v[192:195], v[124:127]
	v_mfma_f32_16x16x32_bf16 v[128:131], v[212:215], v[192:195], v[128:131]
	v_mfma_f32_16x16x32_bf16 v[132:135], v[200:203], v[196:199], v[132:135]
	v_mfma_f32_16x16x32_bf16 v[136:139], v[204:207], v[196:199], v[136:139]
	v_mfma_f32_16x16x32_bf16 v[140:143], v[208:211], v[196:199], v[140:143]
	v_mfma_f32_16x16x32_bf16 v[144:147], v[212:215], v[196:199], v[144:147]
	v_lshlrev_b32_e32 v234, 8, v236
	v_lshl_add_u64 v[238:239], v[234:235], 0, s[92:93]
	v_lshl_add_u64 v[238:239], v[32:33], 3, v[238:239]
	global_load_dwordx4 v[8:11], v[238:239], off
	global_load_dwordx4 v[12:15], v[238:239], off offset:16
	global_load_dwordx4 v[16:19], v[238:239], off offset:32
	global_load_dwordx4 v[20:23], v[238:239], off offset:48
	s_nop 7
	ds_write_b128 v240, v[84:87] offset:0
	ds_write_b128 v240, v[88:91] offset:1024
	ds_write_b128 v240, v[92:95] offset:2048
	ds_write_b128 v240, v[96:99] offset:3072
	ds_write_b128 v240, v[100:103] offset:4096
	ds_write_b128 v240, v[104:107] offset:5120
	ds_write_b128 v240, v[108:111] offset:6144
	ds_write_b128 v240, v[112:115] offset:7168
	ds_write_b128 v240, v[116:119] offset:8192
	ds_write_b128 v240, v[120:123] offset:9216
	ds_write_b128 v240, v[124:127] offset:10240
	ds_write_b128 v240, v[128:131] offset:11264
	ds_write_b128 v240, v[132:135] offset:12288
	ds_write_b128 v240, v[136:139] offset:13312
	ds_write_b128 v240, v[140:143] offset:14336
	ds_write_b128 v240, v[144:147] offset:15360
	s_waitcnt lgkmcnt(0)
	s_barrier
	ds_read_b128 v[148:151], v241 offset:0
	ds_read_b128 v[152:155], v241 offset:16384
	ds_read_b128 v[156:159], v241 offset:32768
	ds_read_b128 v[160:163], v241 offset:49152
	ds_read_b128 v[164:167], v241 offset:1024
	ds_read_b128 v[168:171], v241 offset:17408
	ds_read_b128 v[172:175], v241 offset:33792
	ds_read_b128 v[176:179], v241 offset:50176
	ds_read_b128 v[180:183], v241 offset:2048
	ds_read_b128 v[184:187], v241 offset:18432
	ds_read_b128 v[188:191], v241 offset:34816
	ds_read_b128 v[192:195], v241 offset:51200
	ds_read_b128 v[196:199], v241 offset:3072
	ds_read_b128 v[200:203], v241 offset:19456
	ds_read_b128 v[204:207], v241 offset:35840
	ds_read_b128 v[208:211], v241 offset:52224
	v_add_u32_e32 v244, 0x8000, v236
	v_mad_i64_i32 v[242:243], s[12:13], v244, s10, v[38:39]
	v_lshl_add_u64 v[242:243], s[0:1], 1, v[242:243]
	v_lshl_add_u64 v[242:243], v[242:243], 0, v[32:33]
	v_mbcnt_lo_u32_b32 v245, -1, 0
	v_mbcnt_hi_u32_b32 v245, -1, v245
	v_xor_b32_e32 v246, 16, v245
	v_xor_b32_e32 v247, 32, v245
	v_lshlrev_b32_e32 v246, 2, v246
	v_lshlrev_b32_e32 v247, 2, v247
	s_waitcnt lgkmcnt(0)
	s_barrier
; __device__ __forceinline__ unsigned cvt_pk_bf16(float lo, float hi) { unsigned r; asm volatile("v_cvt_pk_bf16_f32 %0, %1, %2" : "=v"(r) : "v"(lo), "v"(hi)); return r; }
; __device__ __forceinline__ float rs_sample(const float* ssps, int srow) { return rs_from(ssps + (size_t)srow * 64, 16, 1.0f / 1024.0f); }
;     __device__ __forceinline__ void operator()(const f32x4 (&acc)[2], int srow, int cgp, int kq) const { one(acc[0], srow, 2 * cgp, kq); one(acc[1], srow, 2 * cgp + 1, kq); }
; __device__ __forceinline__ float rs_from(const float* p, int n4, float inv_n) {
;     float s = 0.f;
;     for (int i = 0; i < n4; ++i) { const f32x4 v = *(const f32x4*)(p + 4 * i); s += (v[0] + v[1]) + (v[2] + v[3]); }
;     return rsqrtf(s * inv_n + EPS);
;     __device__ __forceinline__ void operator()(const f32x4 (&acc)[4], int srow, int cgp, int kq) const {
;         const float rs = rs_sample(ssps, srow);
; #pragma unroll
;         for (int q = 0; q < 2; ++q) { f32x4 o;
; #pragma unroll
;             for (int j = 0; j < 4; ++j) { const float g = acc[2 * q][j] * rs, up = acc[2 * q + 1][j] * rs; o[j] = g * __builtin_amdgcn_rcpf(1.0f + __expf(-g)) * up; }
;             u32x2 w; w.x = cvt_pk_bf16(o[0], o[1]); w.y = cvt_pk_bf16(o[2], o[3]);
;             *(u32x2*)(act + (size_t)(TP + srow) * FF + (2 * cgp + q) * 16 + 4 * kq) = w; }
	v_add_f32_e32 v84, v148, v152
	v_add_f32_e32 v85, v149, v153
	v_add_f32_e32 v86, v150, v154
	v_add_f32_e32 v87, v151, v155
	v_add_f32_e32 v84, v84, v156
	v_add_f32_e32 v85, v85, v157
	v_add_f32_e32 v86, v86, v158
	v_add_f32_e32 v87, v87, v159
	v_add_f32_e32 v84, v84, v160
	v_add_f32_e32 v85, v85, v161
	v_add_f32_e32 v86, v86, v162
	v_add_f32_e32 v87, v87, v163
	v_add_f32_e32 v88, v164, v168
	v_add_f32_e32 v89, v165, v169
	v_add_f32_e32 v90, v166, v170
	v_add_f32_e32 v91, v167, v171
	v_add_f32_e32 v88, v88, v172
	v_add_f32_e32 v89, v89, v173
	v_add_f32_e32 v90, v90, v174
	v_add_f32_e32 v91, v91, v175
	v_add_f32_e32 v88, v88, v176
	v_add_f32_e32 v89, v89, v177
	v_add_f32_e32 v90, v90, v178
	v_add_f32_e32 v91, v91, v179
	v_add_f32_e32 v92, v180, v184
	v_add_f32_e32 v93, v181, v185
	v_add_f32_e32 v94, v182, v186
	v_add_f32_e32 v95, v183, v187
	v_add_f32_e32 v92, v92, v188
	v_add_f32_e32 v93, v93, v189
	v_add_f32_e32 v94, v94, v190
	v_add_f32_e32 v95, v95, v191
	v_add_f32_e32 v92, v92, v192
	v_add_f32_e32 v93, v93, v193
	v_add_f32_e32 v94, v94, v194
	v_add_f32_e32 v95, v95, v195
	v_add_f32_e32 v96, v196, v200
	v_add_f32_e32 v97, v197, v201
	v_add_f32_e32 v98, v198, v202
	v_add_f32_e32 v99, v199, v203
	v_add_f32_e32 v96, v96, v204
	v_add_f32_e32 v97, v97, v205
	v_add_f32_e32 v98, v98, v206
	v_add_f32_e32 v99, v99, v207
	v_add_f32_e32 v96, v96, v208
	v_add_f32_e32 v97, v97, v209
	v_add_f32_e32 v98, v98, v210
	v_add_f32_e32 v99, v99, v211
	s_waitcnt vmcnt(0)
	v_add_f32_e32 v8, v8, v9
	v_add_f32_e32 v10, v10, v11
	v_add_f32_e32 v8, v8, v10
	v_add_f32_e32 v12, v12, v13
	v_add_f32_e32 v14, v14, v15
	v_add_f32_e32 v12, v12, v14
	v_add_f32_e32 v16, v16, v17
	v_add_f32_e32 v18, v18, v19
	v_add_f32_e32 v16, v16, v18
	v_add_f32_e32 v20, v20, v21
	v_add_f32_e32 v22, v22, v23
	v_add_f32_e32 v20, v20, v22
	v_add_f32_e32 v8, v8, v12
	v_add_f32_e32 v16, v16, v20
	v_add_f32_e32 v8, v8, v16
	ds_bpermute_b32 v9, v246, v8
	s_waitcnt lgkmcnt(0)
	v_add_f32_e32 v8, v8, v9
	ds_bpermute_b32 v9, v247, v8
	s_waitcnt lgkmcnt(0)
	v_add_f32_e32 v8, v8, v9
	v_fmamk_f32 v8, v8, 0x3a800000, v54
	v_rsq_f32_e32 v8, v8
	s_nop 0
	v_pk_mul_f32 v[84:85], v[84:85], v[8:9] op_sel_hi:[1,0]
	v_pk_mul_f32 v[86:87], v[86:87], v[8:9] op_sel_hi:[1,0]
	v_pk_mul_f32 v[88:89], v[88:89], v[8:9] op_sel_hi:[1,0]
	v_pk_mul_f32 v[90:91], v[90:91], v[8:9] op_sel_hi:[1,0]
	v_pk_mul_f32 v[92:93], v[92:93], v[8:9] op_sel_hi:[1,0]
	v_pk_mul_f32 v[94:95], v[94:95], v[8:9] op_sel_hi:[1,0]
	v_pk_mul_f32 v[96:97], v[96:97], v[8:9] op_sel_hi:[1,0]
	v_pk_mul_f32 v[98:99], v[98:99], v[8:9] op_sel_hi:[1,0]
	v_mul_f32_e32 v0, 0xbfb8aa3b, v84
	v_mul_f32_e32 v1, 0xbfb8aa3b, v85
	v_mul_f32_e32 v2, 0xbfb8aa3b, v86
	v_mul_f32_e32 v3, 0xbfb8aa3b, v87
	v_mul_f32_e32 v4, 0xbfb8aa3b, v92
	v_mul_f32_e32 v5, 0xbfb8aa3b, v93
	v_mul_f32_e32 v6, 0xbfb8aa3b, v94
	v_mul_f32_e32 v7, 0xbfb8aa3b, v95
	v_exp_f32_e32 v0, v0
	v_exp_f32_e32 v1, v1
	v_exp_f32_e32 v2, v2
	v_exp_f32_e32 v3, v3
	v_exp_f32_e32 v4, v4
	v_exp_f32_e32 v5, v5
	v_exp_f32_e32 v6, v6
	v_exp_f32_e32 v7, v7
	v_add_f32_e32 v0, 1.0, v0
	v_add_f32_e32 v1, 1.0, v1
	v_add_f32_e32 v2, 1.0, v2
	v_add_f32_e32 v3, 1.0, v3
	v_add_f32_e32 v4, 1.0, v4
	v_add_f32_e32 v5, 1.0, v5
	v_add_f32_e32 v6, 1.0, v6
	v_add_f32_e32 v7, 1.0, v7
	v_rcp_f32_e32 v0, v0
	v_rcp_f32_e32 v1, v1
	v_rcp_f32_e32 v2, v2
	v_rcp_f32_e32 v3, v3
	v_rcp_f32_e32 v4, v4
	v_rcp_f32_e32 v5, v5
	v_rcp_f32_e32 v6, v6
	v_rcp_f32_e32 v7, v7
	v_mul_f32_e32 v0, v84, v0
	v_mul_f32_e32 v1, v85, v1
	v_mul_f32_e32 v2, v86, v2
	v_mul_f32_e32 v3, v87, v3
	v_mul_f32_e32 v4, v92, v4
	v_mul_f32_e32 v5, v93, v5
	v_mul_f32_e32 v6, v94, v6
	v_mul_f32_e32 v7, v95, v7
	v_mul_f32_e32 v0, v88, v0
	v_mul_f32_e32 v1, v89, v1
	v_mul_f32_e32 v2, v90, v2
	v_mul_f32_e32 v3, v91, v3
	v_mul_f32_e32 v4, v96, v4
	v_mul_f32_e32 v5, v97, v5
	v_mul_f32_e32 v6, v98, v6
	v_mul_f32_e32 v7, v99, v7
	v_cvt_pk_bf16_f32 v24, v0, v1
	v_cvt_pk_bf16_f32 v25, v2, v3
	v_cvt_pk_bf16_f32 v26, v4, v5
	v_cvt_pk_bf16_f32 v27, v6, v7
	global_store_dwordx2 v[242:243], v[24:25], off
	global_store_dwordx2 v[242:243], v[26:27], off offset:32
; #define PG8_BAR __builtin_amdgcn_s_barrier()
;     __host__ __device__ bool next(int i, Unit& u) const {
;         const long L = (long)i * G + c; if (L >= nwg) return false;
;         int wgid = (int)L; { const int q = nwg / NXCD, r = nwg % NXCD, xcd = wgid % NXCD, off = wgid / NXCD; wgid = (xcd < r ? xcd * (q + 1) : r * (q + 1) + (xcd - r) * q) + off; }
;         const int nig = WGM * nN, gid = wgid / nig, fm = gid * WGM, gsz = (nM - fm) < WGM ? (nM - fm) : WGM;
;         u.pm = fm + ((wgid % nig) % gsz); u.pn = (wgid % nig) / gsz; return true;
; template <class Epi, class Sched, bool ALIGN_EPI = false, bool SP2 = false>
; __device__ __forceinline__ void gemm_phase(PG8_LAS unsigned char* lds, const Gemm g, const Sched& S, const Epi& E) {
;     const int tid = threadIdx.x, wid = __builtin_amdgcn_readfirstlane(tid >> 6), lane = tid & 63, wr = wid >> 2, wc = wid & 3, fr = lane & 15, fq = lane >> 4;
;     const int K = g.K, nt = K / BK;
;     unsigned voffA[2], voffB[2];
; #pragma unroll
;     for (int i = 0; i < 2; ++i) { int R, C; stage_rc(tid * 16 + i * 8192, R, C); const int Rb = Epi::PERM ? ((R & ~31) + perm32(R & 31)) : R;
;         voffA[i] = (unsigned)(R * K + C) * 2u; voffB[i] = (unsigned)(Rb * K + C) * 2u; }
;     const size_t kstep = (size_t)(BK * 2);
;     const size_t hstep = (size_t)HALF * K * 2;
;     const size_t tstep = 2 * hstep;
;     const unsigned ldsw = (unsigned)wid * 1024u;
;     const int aoff = lds_byte(wr * 64 + fr, fq * 8), boff = lds_byte(wc * 32 + fr, fq * 8);
;     ...
;     Unit cur, nxt; int ui = 0;
;     if (!S.next(0, cur)) return;
;     f32x4 acc[2][2][4][2];
; #pragma unroll
;     for (int a = 0; a < 2; ++a)
; #pragma unroll
;         for (int b = 0; b < 2; ++b)
; #pragma unroll
;             for (int m = 0; m < 4; ++m)
; #pragma unroll
;                 for (int n = 0; n < 2; ++n) acc[a][b][m][n] = (f32x4){0.f, 0.f, 0.f, 0.f};
;     bf16x8 At[4][2], B0[2][2], B1[2][2];
;     const char* cA = (const char*)g.A + (size_t)cur.pm * tstep; const char* cB = (const char*)g.Bt + (size_t)cur.pn * tstep;
;     S.a_ready(cur);
;     if constexpr (SP2) {
;         PG8_STAGE(PG8_SB(0, 0), cB, voffB); PG8_STAGE(PG8_SB(0, 1), cB + hstep, voffB); PG8_STAGE(PG8_SA(0, 0), cA, voffA); PG8_STAGE(PG8_SA(0, 1), cA + hstep, voffA);
;         if (wr == 1) PG8_BAR;
.Lsku_end1:
	s_cbranch_scc1 .LBB0_1302
.LBB0_1303:
	s_movk_i32 s0, 0x400
	s_cmpk_gt_i32 s18, 0xaff
	v_readfirstlane_b32 s3, v254
	s_cbranch_scc1 .LBB0_1324
	v_lshrrev_b32_e32 v0, 5, v254
	v_lshrrev_b32_e32 v2, 1, v254
	v_and_b32_e32 v0, 4, v0
	v_bfe_u32 v1, v254, 2, 2
	v_and_b32_e32 v14, 24, v2
	v_or3_b32 v0, v0, v1, v14
	v_lshlrev_b32_e32 v1, 4, v254
	v_add_u32_e32 v2, 0x2000, v1
	v_lshrrev_b32_e32 v2, 7, v2
	v_and_b32_e32 v4, 32, v254
	s_movk_i32 s2, 0xe0
	v_bitop3_b32 v12, v1, v4, 48 bitop3:0x6c
	v_and_b32_e32 v13, 64, v254
	v_and_b32_e32 v15, 0xf0, v2
	v_bfe_u32 v16, v254, 2, 4
	v_and_or_b32 v3, v2, s2, v0
	v_or_b32_e32 v1, v12, v13
	v_or_b32_e32 v2, v15, v16
	v_lshrrev_b32_e32 v1, 1, v1
	v_mul_lo_u32 v2, s0, v2
	v_add_lshl_u32 v130, v2, v1, 1
	v_lshrrev_b32_e32 v2, 3, v254
	s_movk_i32 s2, 0x60
	s_ashr_i32 s17, s18, 31
	v_and_or_b32 v0, v2, s2, v0
	s_lshr_b32 s2, s17, 29
	s_add_i32 s2, s18, s2
	s_lshr_b32 s20, s3, 6
	s_ashr_i32 s1, s0, 31
	s_ashr_i32 s12, s2, 3
	s_and_b32 s2, s2, -8
	s_lshr_b32 s21, s3, 8
	s_lshl_b64 s[8:9], s[0:1], 8
	s_lshl_b64 s[10:11], s[0:1], 9
	s_lshl_b32 s16, s20, 10
	s_sub_i32 s2, s18, s2
	s_cmp_lt_i32 s2, 0
	s_movk_i32 s19, 0x161
	s_cselect_b32 s13, s19, 0x160
	s_mul_i32 s2, s13, s2
	s_add_i32 s2, s2, s12
	s_mul_hi_i32 s12, s2, 0x2e8ba2e9
	s_lshr_b32 s13, s12, 31
	s_ashr_i32 s12, s12, 5
	s_add_i32 s12, s12, s13
	s_lshl_b32 s13, s12, 3
	s_mulk_i32 s12, 0xb0
	s_sub_i32 s12, s2, s12
	s_sext_i32_i16 s2, s12
	s_bfe_u32 s2, s2, 0x3001c
	s_add_i32 s14, s12, s2
	s_sext_i32_i16 s22, s14
	s_and_b32 s14, s14, 0xfff8
	s_sub_i32 s12, s12, s14
	s_sext_i32_i16 s12, s12
	s_add_i32 s60, s13, s12
	s_ashr_i32 s12, s60, 31
	s_mul_i32 s12, s10, s12
	s_mul_hi_u32 s13, s10, s60
	s_add_i32 s14, s13, s12
	s_lshr_b64 s[12:13], s[0:1], 23
	s_lshr_b32 s2, s22, 3
	s_mul_i32 s13, s12, s60
	s_add_i32 s23, s14, s13
	s_bfe_i64 s[14:15], s[2:3], 0x100000
	s_ashr_i32 s13, s22, 3
	s_mul_hi_u32 s14, s10, s13
	s_mul_i32 s15, s10, s15
	s_add_i32 s14, s14, s15
	s_mul_i32 s12, s12, s13
	s_add_i32 s14, s14, s12
	s_mul_i32 s12, s10, s13
	s_add_u32 s28, s6, s12
	v_mul_lo_u32 v0, s0, v0
	s_addc_u32 s29, s7, s14
	s_add_i32 s30, s16, 0
	v_add_lshl_u32 v132, v0, v1, 1
	s_add_i32 m0, s30, 0x10000
	v_mul_lo_u32 v3, s0, v3
	global_load_lds_dwordx4 v132, s[28:29]
	s_add_i32 m0, s30, 0x12000
	v_add_lshl_u32 v128, v3, v1, 1
	s_add_u32 s12, s28, s8
	global_load_lds_dwordx4 v128, s[28:29]
	s_addc_u32 s13, s29, s9
	s_add_i32 m0, s30, 0x14000
	v_and_b32_e32 v17, 0x70, v2
	s_mul_i32 s24, s10, s60
	global_load_lds_dwordx4 v132, s[12:13]
	s_add_i32 m0, s30, 0x16000
	v_or_b32_e32 v0, v17, v16
	s_add_u32 s26, s42, s24
	v_mul_lo_u32 v0, s0, v0
	s_addc_u32 s27, s43, s23
	s_add_i32 s31, s30, 0x2000
	v_add_lshl_u32 v134, v0, v1, 1
	global_load_lds_dwordx4 v128, s[12:13]
	s_mov_b32 m0, s30
	s_add_u32 s14, s26, s8
	global_load_lds_dwordx4 v134, s[26:27]
	s_mov_b32 m0, s31
	s_addc_u32 s15, s27, s9
	s_add_i32 s33, s30, 0x4000
	global_load_lds_dwordx4 v130, s[26:27]
	s_mov_b32 m0, s33
	s_add_i32 s34, s30, 0x6000
	global_load_lds_dwordx4 v134, s[14:15]
	s_mov_b32 m0, s34
	v_mov_b32_e32 v133, 0
	global_load_lds_dwordx4 v130, s[14:15]
	v_mov_b32_e32 v129, v133
	v_mov_b32_e32 v135, v133
	v_mov_b32_e32 v131, v133
	s_cmp_eq_u32 s21, 1
	s_mov_b32 s35, 0
	v_lshl_add_u64 v[8:9], s[28:29], 0, v[132:133]
	v_lshl_add_u64 v[4:5], s[28:29], 0, v[128:129]
	v_lshl_add_u64 v[2:3], s[12:13], 0, v[132:133]
	v_lshl_add_u64 v[0:1], s[12:13], 0, v[128:129]
	v_lshl_add_u64 v[6:7], s[26:27], 0, v[134:135]
	s_cselect_b64 s[12:13], -1, 0
	s_cmp_lg_u32 s21, 1
	v_lshl_add_u64 v[10:11], s[26:27], 0, v[130:131]
	s_cbranch_scc1 .LBB0_1306
	s_barrier

; #define PG8_BAR __builtin_amdgcn_s_barrier()
;     __host__ __device__ bool next(int i, Unit& u) const {
;         const long L = (long)i * G + c; if (L >= nwg) return false;
;         int wgid = (int)L; { const int q = nwg / NXCD, r = nwg % NXCD, xcd = wgid % NXCD, off = wgid / NXCD; wgid = (xcd < r ? xcd * (q + 1) : r * (q + 1) + (xcd - r) * q) + off; }
;         const int nig = WGM * nN, gid = wgid / nig, fm = gid * WGM, gsz = (nM - fm) < WGM ? (nM - fm) : WGM;
;         u.pm = fm + ((wgid % nig) % gsz); u.pn = (wgid % nig) / gsz; return true;
; template <class Epi, class Sched, bool ALIGN_EPI = false, bool SP2 = false>
; __device__ __forceinline__ void gemm_phase(PG8_LAS unsigned char* lds, const Gemm g, const Sched& S, const Epi& E) {
;     const int tid = threadIdx.x, wid = __builtin_amdgcn_readfirstlane(tid >> 6), lane = tid & 63, wr = wid >> 2, wc = wid & 3, fr = lane & 15, fq = lane >> 4;
;     const int K = g.K, nt = K / BK;
;     unsigned voffA[2], voffB[2];
; #pragma unroll
;     for (int i = 0; i < 2; ++i) { int R, C; stage_rc(tid * 16 + i * 8192, R, C); const int Rb = Epi::PERM ? ((R & ~31) + perm32(R & 31)) : R;
;         voffA[i] = (unsigned)(R * K + C) * 2u; voffB[i] = (unsigned)(Rb * K + C) * 2u; }
;     const size_t kstep = (size_t)(BK * 2);
;     const size_t hstep = (size_t)HALF * K * 2;
;     const size_t tstep = 2 * hstep;
;     const unsigned ldsw = (unsigned)wid * 1024u;
;     const int aoff = lds_byte(wr * 64 + fr, fq * 8), boff = lds_byte(wc * 32 + fr, fq * 8);
;     ...
;     Unit cur, nxt; int ui = 0;
;     if (!S.next(0, cur)) return;
;     f32x4 acc[2][2][4][2];
; #pragma unroll
;     for (int a = 0; a < 2; ++a)
; #pragma unroll
;         for (int b = 0; b < 2; ++b)
; #pragma unroll
;             for (int m = 0; m < 4; ++m)
; #pragma unroll
;                 for (int n = 0; n < 2; ++n) acc[a][b][m][n] = (f32x4){0.f, 0.f, 0.f, 0.f};
;     bf16x8 At[4][2], B0[2][2], B1[2][2];
;     const char* cA = (const char*)g.A + (size_t)cur.pm * tstep; const char* cB = (const char*)g.Bt + (size_t)cur.pn * tstep;
;     S.a_ready(cur);
;     if constexpr (SP2) {
;         PG8_STAGE(PG8_SB(0, 0), cB, voffB); PG8_STAGE(PG8_SB(0, 1), cB + hstep, voffB); PG8_STAGE(PG8_SA(0, 0), cA, voffA); PG8_STAGE(PG8_SA(0, 1), cA + hstep, voffA);
;         if (wr == 1) PG8_BAR;
.Lsku_end2:
	s_cbranch_scc1 .LBB0_1492
.LBB0_1493:
	s_movk_i32 s0, 0x400
	s_cmpk_gt_i32 s18, 0xaff
	v_readfirstlane_b32 s3, v254
	s_cbranch_scc1 .LBB0_1514
	v_lshrrev_b32_e32 v0, 5, v254
	v_lshrrev_b32_e32 v2, 1, v254
	v_and_b32_e32 v0, 4, v0
	v_bfe_u32 v1, v254, 2, 2
	v_and_b32_e32 v14, 24, v2
	v_or3_b32 v0, v0, v1, v14
	v_lshlrev_b32_e32 v1, 4, v254
	v_add_u32_e32 v2, 0x2000, v1
	v_lshrrev_b32_e32 v2, 7, v2
	v_and_b32_e32 v4, 32, v254
	s_movk_i32 s2, 0xe0
	v_bitop3_b32 v12, v1, v4, 48 bitop3:0x6c
	v_and_b32_e32 v13, 64, v254
	v_and_b32_e32 v15, 0xf0, v2
	v_bfe_u32 v16, v254, 2, 4
	v_and_or_b32 v3, v2, s2, v0
	v_or_b32_e32 v1, v12, v13
	v_or_b32_e32 v2, v15, v16
	v_lshrrev_b32_e32 v1, 1, v1
	v_mul_lo_u32 v2, s0, v2
	v_add_lshl_u32 v130, v2, v1, 1
	v_lshrrev_b32_e32 v2, 3, v254
	s_movk_i32 s2, 0x60
	s_ashr_i32 s17, s18, 31
	v_and_or_b32 v0, v2, s2, v0
	s_lshr_b32 s2, s17, 29
	s_add_i32 s2, s18, s2
	s_lshr_b32 s20, s3, 6
	s_ashr_i32 s1, s0, 31
	s_ashr_i32 s12, s2, 3
	s_and_b32 s2, s2, -8
	s_lshr_b32 s21, s3, 8
	s_lshl_b64 s[8:9], s[0:1], 8
	s_lshl_b64 s[10:11], s[0:1], 9
	s_lshl_b32 s16, s20, 10
	s_sub_i32 s2, s18, s2
	s_cmp_lt_i32 s2, 0
	s_movk_i32 s19, 0x161
	s_cselect_b32 s13, s19, 0x160
	s_mul_i32 s2, s13, s2
	s_add_i32 s2, s2, s12
	s_mul_hi_i32 s12, s2, 0x2e8ba2e9
	s_lshr_b32 s13, s12, 31
	s_ashr_i32 s12, s12, 5
	s_add_i32 s12, s12, s13
	s_lshl_b32 s13, s12, 3
	s_mulk_i32 s12, 0xb0
	s_sub_i32 s12, s2, s12
	s_sext_i32_i16 s2, s12
	s_bfe_u32 s2, s2, 0x3001c
	s_add_i32 s14, s12, s2
	s_sext_i32_i16 s22, s14
	s_and_b32 s14, s14, 0xfff8
	s_sub_i32 s12, s12, s14
	s_sext_i32_i16 s12, s12
	s_add_i32 s60, s13, s12
	s_ashr_i32 s12, s60, 31
	s_mul_i32 s12, s10, s12
	s_mul_hi_u32 s13, s10, s60
	s_add_i32 s14, s13, s12
	s_lshr_b64 s[12:13], s[0:1], 23
	s_lshr_b32 s2, s22, 3
	s_mul_i32 s13, s12, s60
	s_add_i32 s23, s14, s13
	s_bfe_i64 s[14:15], s[2:3], 0x100000
	s_ashr_i32 s13, s22, 3
	s_mul_hi_u32 s14, s10, s13
	s_mul_i32 s15, s10, s15
	s_add_i32 s14, s14, s15
	s_mul_i32 s12, s12, s13
	s_add_i32 s14, s14, s12
	s_mul_i32 s12, s10, s13
	s_add_u32 s28, s6, s12
	v_mul_lo_u32 v0, s0, v0
	s_addc_u32 s29, s7, s14
	s_add_i32 s30, s16, 0
	v_add_lshl_u32 v132, v0, v1, 1
	s_add_i32 m0, s30, 0x10000
	v_mul_lo_u32 v3, s0, v3
	global_load_lds_dwordx4 v132, s[28:29]
	s_add_i32 m0, s30, 0x12000
	v_add_lshl_u32 v128, v3, v1, 1
	s_add_u32 s12, s28, s8
	global_load_lds_dwordx4 v128, s[28:29]
	s_addc_u32 s13, s29, s9
	s_add_i32 m0, s30, 0x14000
	v_and_b32_e32 v17, 0x70, v2
	s_mul_i32 s24, s10, s60
	global_load_lds_dwordx4 v132, s[12:13]
	s_add_i32 m0, s30, 0x16000
	v_or_b32_e32 v0, v17, v16
	s_add_u32 s26, s42, s24
	v_mul_lo_u32 v0, s0, v0
	s_addc_u32 s27, s43, s23
	s_add_i32 s31, s30, 0x2000
	v_add_lshl_u32 v134, v0, v1, 1
	global_load_lds_dwordx4 v128, s[12:13]
	s_mov_b32 m0, s30
	s_add_u32 s14, s26, s8
	global_load_lds_dwordx4 v134, s[26:27]
	s_mov_b32 m0, s31
	s_addc_u32 s15, s27, s9
	s_add_i32 s33, s30, 0x4000
	global_load_lds_dwordx4 v130, s[26:27]
	s_mov_b32 m0, s33
	s_add_i32 s34, s30, 0x6000
	global_load_lds_dwordx4 v134, s[14:15]
	s_mov_b32 m0, s34
	v_mov_b32_e32 v133, 0
	global_load_lds_dwordx4 v130, s[14:15]
	v_mov_b32_e32 v129, v133
	v_mov_b32_e32 v135, v133
	v_mov_b32_e32 v131, v133
	s_cmp_eq_u32 s21, 1
	s_mov_b32 s35, 0
	v_lshl_add_u64 v[8:9], s[28:29], 0, v[132:133]
	v_lshl_add_u64 v[4:5], s[28:29], 0, v[128:129]
	v_lshl_add_u64 v[2:3], s[12:13], 0, v[132:133]
	v_lshl_add_u64 v[0:1], s[12:13], 0, v[128:129]
	v_lshl_add_u64 v[6:7], s[26:27], 0, v[134:135]
	s_cselect_b64 s[12:13], -1, 0
	s_cmp_lg_u32 s21, 1
	v_lshl_add_u64 v[10:11], s[26:27], 0, v[130:131]
	s_cbranch_scc1 .LBB0_1496
	s_barrier

; #define PG8_STAGE(bufoff, gbase, voff) do { _Pragma("unroll") for (int _i = 0; _i < 2; ++_i) \
;         __builtin_amdgcn_global_load_lds((const unsigned*)((const char*)(gbase) + (voff)[_i]), (PG8_LAS unsigned*)(lds + (bufoff) + ldsw + _i * 8192), 16, 0, 0); } while (0)
; #define PG8_BAR __builtin_amdgcn_s_barrier()
; template <class Epi, class Sched, bool ALIGN_EPI = false, bool SP2 = false>
; __device__ __forceinline__ void gemm_phase(PG8_LAS unsigned char* lds, const Gemm g, const Sched& S, const Epi& E) {
;     const int tid = threadIdx.x, wid = __builtin_amdgcn_readfirstlane(tid >> 6), lane = tid & 63, wr = wid >> 2, wc = wid & 3, fr = lane & 15, fq = lane >> 4;
;     const int K = g.K, nt = K / BK;
;     unsigned voffA[2], voffB[2];
; #pragma unroll
;     for (int i = 0; i < 2; ++i) { int R, C; stage_rc(tid * 16 + i * 8192, R, C); const int Rb = Epi::PERM ? ((R & ~31) + perm32(R & 31)) : R;
;         voffA[i] = (unsigned)(R * K + C) * 2u; voffB[i] = (unsigned)(Rb * K + C) * 2u; }
;     const size_t kstep = (size_t)(BK * 2);
;     const size_t hstep = (size_t)HALF * K * 2;
;     const size_t tstep = 2 * hstep;
;     const unsigned ldsw = (unsigned)wid * 1024u;
;     const int aoff = lds_byte(wr * 64 + fr, fq * 8), boff = lds_byte(wc * 32 + fr, fq * 8);
;     ...
;     Unit cur, nxt; int ui = 0;
;     if (!S.next(0, cur)) return;
;     f32x4 acc[2][2][4][2];
; #pragma unroll
;     for (int a = 0; a < 2; ++a)
; #pragma unroll
;         for (int b = 0; b < 2; ++b)
; #pragma unroll
;             for (int m = 0; m < 4; ++m)
; #pragma unroll
;                 for (int n = 0; n < 2; ++n) acc[a][b][m][n] = (f32x4){0.f, 0.f, 0.f, 0.f};
;     bf16x8 At[4][2], B0[2][2], B1[2][2];
;     const char* cA = (const char*)g.A + (size_t)cur.pm * tstep; const char* cB = (const char*)g.Bt + (size_t)cur.pn * tstep;
;     S.a_ready(cur);
;     if constexpr (SP2) {
;         PG8_STAGE(PG8_SB(0, 0), cB, voffB); PG8_STAGE(PG8_SB(0, 1), cB + hstep, voffB); PG8_STAGE(PG8_SA(0, 0), cA, voffA); PG8_STAGE(PG8_SA(0, 1), cA + hstep, voffA);
;         if (wr == 1) PG8_BAR;
.Lsku_end3:
	s_cbranch_scc1 .LBB0_2466
.LBB0_2467:
	s_movk_i32 s0, 0x400
	s_cmpk_gt_i32 s18, 0xaff
	v_readfirstlane_b32 s3, v254
	s_cbranch_scc1 .LBB0_2488
	v_lshrrev_b32_e32 v0, 5, v254
	v_lshrrev_b32_e32 v2, 1, v254
	v_and_b32_e32 v0, 4, v0
	v_bfe_u32 v1, v254, 2, 2
	v_and_b32_e32 v14, 24, v2
	v_or3_b32 v0, v0, v1, v14
	v_lshlrev_b32_e32 v1, 4, v254
	v_add_u32_e32 v2, 0x2000, v1
	v_lshrrev_b32_e32 v2, 7, v2
	v_and_b32_e32 v4, 32, v254
	s_movk_i32 s2, 0xe0
	v_bitop3_b32 v12, v1, v4, 48 bitop3:0x6c
	v_and_b32_e32 v13, 64, v254
	v_and_b32_e32 v15, 0xf0, v2
	v_bfe_u32 v16, v254, 2, 4
	v_and_or_b32 v3, v2, s2, v0
	v_or_b32_e32 v1, v12, v13
	v_or_b32_e32 v2, v15, v16
	v_lshrrev_b32_e32 v1, 1, v1
	v_mul_lo_u32 v2, s0, v2
	v_add_lshl_u32 v130, v2, v1, 1
	v_lshrrev_b32_e32 v2, 3, v254
	s_movk_i32 s2, 0x60
	s_ashr_i32 s17, s18, 31
	v_and_or_b32 v0, v2, s2, v0
	s_lshr_b32 s2, s17, 29
	s_add_i32 s2, s18, s2
	s_lshr_b32 s20, s3, 6
	s_ashr_i32 s1, s0, 31
	s_ashr_i32 s12, s2, 3
	s_and_b32 s2, s2, -8
	s_lshr_b32 s21, s3, 8
	s_lshl_b64 s[8:9], s[0:1], 8
	s_lshl_b64 s[10:11], s[0:1], 9
	s_lshl_b32 s16, s20, 10
	s_sub_i32 s2, s18, s2
	s_cmp_lt_i32 s2, 0
	s_movk_i32 s19, 0x161
	s_cselect_b32 s13, s19, 0x160
	s_mul_i32 s2, s13, s2
	s_add_i32 s2, s2, s12
	s_mul_hi_i32 s12, s2, 0x2e8ba2e9
	s_lshr_b32 s13, s12, 31
	s_ashr_i32 s12, s12, 5
	s_add_i32 s12, s12, s13
	s_lshl_b32 s13, s12, 3
	s_mulk_i32 s12, 0xb0
	s_sub_i32 s12, s2, s12
	s_sext_i32_i16 s2, s12
	s_bfe_u32 s2, s2, 0x3001c
	s_add_i32 s14, s12, s2
	s_sext_i32_i16 s22, s14
	s_and_b32 s14, s14, 0xfff8
	s_sub_i32 s12, s12, s14
	s_sext_i32_i16 s12, s12
	s_add_i32 s58, s13, s12
	s_ashr_i32 s12, s58, 31
	s_mul_i32 s12, s10, s12
	s_mul_hi_u32 s13, s10, s58
	s_add_i32 s14, s13, s12
	s_lshr_b64 s[12:13], s[0:1], 23
	s_lshr_b32 s2, s22, 3
	s_mul_i32 s13, s12, s58
	s_add_i32 s23, s14, s13
	s_bfe_i64 s[14:15], s[2:3], 0x100000
	s_ashr_i32 s13, s22, 3
	s_mul_hi_u32 s14, s10, s13
	s_mul_i32 s15, s10, s15
	s_add_i32 s14, s14, s15
	s_mul_i32 s12, s12, s13
	s_add_i32 s14, s14, s12
	s_mul_i32 s12, s10, s13
	s_add_u32 s28, s6, s12
	v_mul_lo_u32 v0, s0, v0
	s_addc_u32 s29, s7, s14
	s_add_i32 s30, s16, 0
	v_add_lshl_u32 v132, v0, v1, 1
	s_add_i32 m0, s30, 0x10000
	v_mul_lo_u32 v3, s0, v3
	global_load_lds_dwordx4 v132, s[28:29]
	s_add_i32 m0, s30, 0x12000
	v_add_lshl_u32 v128, v3, v1, 1
	s_add_u32 s12, s28, s8
	global_load_lds_dwordx4 v128, s[28:29]
	s_addc_u32 s13, s29, s9
	s_add_i32 m0, s30, 0x14000
	v_and_b32_e32 v17, 0x70, v2
	s_mul_i32 s24, s10, s58
	global_load_lds_dwordx4 v132, s[12:13]
	s_add_i32 m0, s30, 0x16000
	v_or_b32_e32 v0, v17, v16
	s_add_u32 s26, s42, s24
	v_mul_lo_u32 v0, s0, v0
	s_addc_u32 s27, s43, s23
	s_add_i32 s31, s30, 0x2000
	v_add_lshl_u32 v134, v0, v1, 1
	global_load_lds_dwordx4 v128, s[12:13]
	s_mov_b32 m0, s30
	s_add_u32 s14, s26, s8
	global_load_lds_dwordx4 v134, s[26:27]
	s_mov_b32 m0, s31
	s_addc_u32 s15, s27, s9
	s_add_i32 s33, s30, 0x4000
	global_load_lds_dwordx4 v130, s[26:27]
	s_mov_b32 m0, s33
	s_add_i32 s34, s30, 0x6000
	global_load_lds_dwordx4 v134, s[14:15]
	s_mov_b32 m0, s34
	v_mov_b32_e32 v133, 0
	global_load_lds_dwordx4 v130, s[14:15]
	v_mov_b32_e32 v129, v133
	v_mov_b32_e32 v135, v133
	v_mov_b32_e32 v131, v133
	s_cmp_eq_u32 s21, 1
	s_mov_b32 s35, 0
	v_lshl_add_u64 v[8:9], s[28:29], 0, v[132:133]
	v_lshl_add_u64 v[4:5], s[28:29], 0, v[128:129]
	v_lshl_add_u64 v[2:3], s[12:13], 0, v[132:133]
	v_lshl_add_u64 v[0:1], s[12:13], 0, v[128:129]
	v_lshl_add_u64 v[6:7], s[26:27], 0, v[134:135]
	s_cselect_b64 s[12:13], -1, 0
	s_cmp_lg_u32 s21, 1
	v_lshl_add_u64 v[10:11], s[26:27], 0, v[130:131]
	s_cbranch_scc1 .LBB0_2470
	s_barrier
